# v71 + branch-free retention decay factors + phase-C K/V slice prefetch + K-head sum-of-squares via permlane swaps (all bit-identical)
# baseline (speedup 1.0000x reference)
.LBB0_421:
	v_mov_b32_e32 v58, v0
	s_load_dwordx4 s[4:7], s[16:17], 0x98
	v_and_b32_e32 v8, 3, v1
	v_lshlrev_b32_e32 v2, 2, v8
	v_and_b32_e32 v7, 3, v45
	s_waitcnt lgkmcnt(0)
	global_load_dword v6, v2, s[4:5]
	s_nop 0
	global_load_dword v2, v2, s[6:7]
	v_lshlrev_b32_e32 v232, 3, v0
	v_and_b32_e32 v232, 56, v232
	v_lshlrev_b32_e32 v232, 1, v232
	v_and_b32_e32 v233, 3, v1
	v_lshl_or_b32 v232, v233, 7, v232
	v_mov_b32_e32 v233, 0
	v_lshl_add_u64 v[234:235], s[22:23], 0, v[232:233]
	v_bfe_u32 v232, v0, 3, 5
	v_ashrrev_i32_e32 v233, 2, v1
	v_lshl_or_b32 v232, v233, 7, v232
	v_mad_i64_i32 v[234:235], s[2:3], v232, s54, v[234:235]
	global_load_dwordx4 v[200:203], v[234:235], off offset:2880
	global_load_dwordx4 v[204:207], v[234:235], off offset:3392
	v_add_co_u32_e32 v234, vcc, 0x22800, v234
	s_nop 1
	v_addc_co_u32_e32 v235, vcc, 0, v235, vcc
	global_load_dwordx4 v[208:211], v[234:235], off offset:2880
	global_load_dwordx4 v[212:215], v[234:235], off offset:3392
	v_add_co_u32_e32 v234, vcc, 0x22800, v234
	s_nop 1
	v_addc_co_u32_e32 v235, vcc, 0, v235, vcc
	global_load_dwordx4 v[216:219], v[234:235], off offset:2880
	global_load_dwordx4 v[220:223], v[234:235], off offset:3392
	v_add_co_u32_e32 v234, vcc, 0x22800, v234
	s_nop 1
	v_addc_co_u32_e32 v235, vcc, 0, v235, vcc
	global_load_dwordx4 v[224:227], v[234:235], off offset:2880
	global_load_dwordx4 v[228:231], v[234:235], off offset:3392
	v_lshlrev_b16_e32 v12, 5, v7
	v_lshlrev_b32_e32 v16, 5, v7
	v_ashrrev_i32_e32 v13, 2, v1
	s_load_dwordx2 s[4:5], s[16:17], 0x68
	s_load_dwordx2 s[6:7], s[16:17], 0x90
	v_bfe_u32 v59, v58, 6, 2
	v_and_b32_e32 v26, 63, v58
	s_mov_b32 s67, 0
	s_waitcnt vmcnt(9)
	v_mul_f32_e32 v7, 0xbfb8aa3b, v6
	s_waitcnt vmcnt(8)
	v_mul_f32_e32 v9, 0xbfb8aa3b, v2
	v_fma_f32 v10, v6, s33, -v7
	v_rndne_f32_e32 v11, v7
	v_fma_f32 v14, v2, s33, -v9
	v_rndne_f32_e32 v15, v9
	v_fmac_f32_e32 v10, 0xb2a5705f, v6
	v_sub_f32_e32 v7, v7, v11
	v_fmac_f32_e32 v14, 0xb2a5705f, v2
	v_sub_f32_e32 v9, v9, v15
	v_add_f32_e32 v7, v7, v10
	v_cvt_i32_f32_e32 v11, v11
	v_add_f32_e32 v9, v9, v14
	v_exp_f32_e32 v7, v7
	v_cvt_i32_f32_e32 v15, v15
	v_exp_f32_e32 v9, v9
	v_cmp_nlt_f32_e32 vcc, s48, v6
	v_ldexp_f32 v7, v7, v11
	v_ldexp_f32 v9, v9, v15
	v_cndmask_b32_e32 v7, 0, v7, vcc
	v_cmp_nlt_f32_e32 vcc, s48, v2
	s_nop 1
	v_cndmask_b32_e32 v9, 0, v9, vcc
	v_cmp_ngt_f32_e32 vcc, s49, v6
	s_nop 1
	v_cndmask_b32_e32 v14, v46, v7, vcc
	v_cmp_ngt_f32_e32 vcc, s49, v2
	v_add_f32_e32 v2, 1.0, v14
	v_frexp_mant_f32_e32 v18, v2
	v_cndmask_b32_e32 v15, v46, v9, vcc
	v_add_f32_e32 v17, 1.0, v15
	v_add_f32_e32 v9, -1.0, v2
	v_cvt_f64_f32_e32 v[6:7], v2
	v_cvt_f64_f32_e32 v[10:11], v17
	v_sub_f32_e32 v21, v9, v2
	v_frexp_exp_i32_f64_e32 v6, v[6:7]
	v_cmp_gt_f32_e32 vcc, s51, v18
	v_sub_f32_e32 v9, v14, v9
	v_frexp_exp_i32_f64_e32 v10, v[10:11]
	v_add_f32_e32 v11, 1.0, v21
	v_subbrev_co_u32_e32 v6, vcc, 0, v6, vcc
	v_add_f32_e32 v19, -1.0, v17
	v_add_f32_e32 v9, v9, v11
	v_sub_u32_e32 v11, 0, v6
	v_sub_f32_e32 v7, v19, v17
	v_cvt_f32_i32_e32 v6, v6
	v_ldexp_f32 v2, v2, v11
	v_sub_f32_e32 v19, v15, v19
	v_add_f32_e32 v7, 1.0, v7
	v_ldexp_f32 v9, v9, v11
	v_add_f32_e32 v11, -1.0, v2
	v_add_f32_e32 v18, 1.0, v2
	v_add_f32_e32 v7, v19, v7
	v_add_f32_e32 v19, 1.0, v11
	v_add_f32_e32 v21, -1.0, v18
	v_sub_f32_e32 v19, v2, v19
	v_sub_f32_e32 v2, v2, v21
	v_mul_f32_e32 v21, 0x3f317218, v6
	v_add_f32_e32 v19, v9, v19
	v_add_f32_e32 v2, v9, v2
	v_fma_f32 v9, v6, s52, -v21
	v_add_f32_e32 v22, v11, v19
	v_add_f32_e32 v23, v18, v2
	v_fmac_f32_e32 v9, 0xb102e308, v6
	v_sub_f32_e32 v6, v11, v22
	v_sub_f32_e32 v11, v18, v23
	v_rcp_f32_e32 v18, v23
	v_add_f32_e32 v24, v21, v9
	v_add_f32_e32 v2, v2, v11
	v_sub_f32_e32 v11, v24, v21
	v_sub_f32_e32 v9, v9, v11
	v_mul_f32_e32 v11, v22, v18
	v_add_f32_e32 v6, v19, v6
	v_mul_f32_e32 v19, v23, v11
	v_fma_f32 v21, v11, v23, -v19
	v_fmac_f32_e32 v21, v11, v2
	v_add_f32_e32 v25, v19, v21
	v_sub_f32_e32 v27, v22, v25
	v_sub_f32_e32 v19, v25, v19
	v_sub_f32_e32 v22, v22, v27
	v_sub_f32_e32 v19, v19, v21
	v_sub_f32_e32 v21, v22, v25
	v_add_f32_e32 v6, v6, v21
	v_add_f32_e32 v6, v19, v6
	v_add_f32_e32 v19, v27, v6
	v_mul_f32_e32 v21, v18, v19
	v_sub_f32_e32 v22, v27, v19
	v_mul_f32_e32 v25, v23, v21
	v_add_f32_e32 v6, v6, v22
	v_add_f32_e32 v22, v11, v21
	v_fma_f32 v23, v21, v23, -v25
	v_sub_f32_e32 v11, v22, v11
	v_fmac_f32_e32 v23, v21, v2
	v_sub_f32_e32 v2, v21, v11
	v_add_f32_e32 v11, v25, v23
	v_sub_f32_e32 v21, v11, v25
	v_sub_f32_e32 v25, v19, v11
	v_sub_f32_e32 v19, v19, v25
	v_sub_f32_e32 v11, v19, v11
	v_sub_f32_e32 v21, v21, v23
	v_add_f32_e32 v6, v6, v11
	v_add_f32_e32 v6, v21, v6
	v_add_f32_e32 v6, v25, v6
	v_mul_f32_e32 v6, v18, v6
	v_add_f32_e32 v2, v2, v6
	v_add_f32_e32 v6, v22, v2
	v_mul_f32_e32 v11, v6, v6
	v_fmamk_f32 v21, v11, 0x3e9b6dac, v47
	v_sub_f32_e32 v18, v6, v22
	v_ldexp_f32 v19, v6, 1
	v_mul_f32_e32 v6, v6, v11
	v_fmaak_f32 v11, v11, v21, 0x3f2aaada
	v_mul_f32_e32 v6, v6, v11
	v_add_f32_e32 v11, v19, v6
	v_sub_f32_e32 v2, v2, v18
	v_sub_f32_e32 v18, v11, v19
	v_ldexp_f32 v2, v2, 1
	v_sub_f32_e32 v6, v6, v18
	v_add_f32_e32 v2, v2, v6
	v_add_f32_e32 v6, v11, v2
	v_sub_f32_e32 v11, v6, v11
	v_add_f32_e32 v18, v24, v6
	v_sub_f32_e32 v2, v2, v11
	v_sub_f32_e32 v11, v18, v24
	v_sub_f32_e32 v19, v18, v11
	v_sub_f32_e32 v6, v6, v11
	v_add_f32_e32 v11, v9, v2
	v_sub_f32_e32 v19, v24, v19
	v_sub_f32_e32 v21, v11, v9
	v_add_f32_e32 v6, v6, v19
	v_sub_f32_e32 v19, v11, v21
	v_sub_f32_e32 v2, v2, v21
	v_sub_f32_e32 v9, v9, v19
	v_add_f32_e32 v6, v11, v6
	v_add_f32_e32 v2, v2, v9
	v_add_f32_e32 v9, v18, v6
	v_sub_f32_e32 v11, v9, v18
	v_sub_f32_e32 v6, v6, v11
	v_add_f32_e32 v2, v2, v6
	v_add_f32_e32 v2, v9, v2
	v_cmp_neq_f32_e32 vcc, s50, v14
	v_frexp_mant_f32_e32 v20, v17
	s_nop 0
	v_cndmask_b32_e32 v2, v46, v2, vcc
	v_cmp_lt_f32_e64 vcc, |v14|, s53
	s_nop 1
	v_cndmask_b32_e32 v9, v2, v14, vcc
	v_cmp_gt_f32_e32 vcc, s51, v20
	s_nop 1
	v_subbrev_co_u32_e32 v14, vcc, 0, v10, vcc
	v_sub_u32_e32 v2, 0, v14
	v_ldexp_f32 v6, v17, v2
	v_ldexp_f32 v2, v7, v2
	v_add_f32_e32 v7, -1.0, v6
	v_add_f32_e32 v17, 1.0, v6
	v_add_f32_e32 v10, 1.0, v7
	v_add_f32_e32 v18, -1.0, v17
	v_sub_f32_e32 v10, v6, v10
	v_sub_f32_e32 v6, v6, v18
	v_add_f32_e32 v10, v2, v10
	v_add_f32_e32 v2, v2, v6
	v_add_f32_e32 v6, v17, v2
	v_rcp_f32_e32 v18, v6
	v_add_f32_e32 v11, v7, v10
	v_sub_f32_e32 v7, v7, v11
	v_add_f32_e32 v7, v10, v7
	v_sub_f32_e32 v10, v17, v6
	v_add_f32_e32 v2, v2, v10
	v_mul_f32_e32 v10, v11, v18
	v_mul_f32_e32 v17, v6, v10
	v_fma_f32 v19, v10, v6, -v17
	v_fmac_f32_e32 v19, v10, v2
	v_add_f32_e32 v20, v17, v19
	v_sub_f32_e32 v21, v11, v20
	v_sub_f32_e32 v11, v11, v21
	v_sub_f32_e32 v17, v20, v17
	v_sub_f32_e32 v11, v11, v20
	v_add_f32_e32 v7, v7, v11
	v_sub_f32_e32 v11, v17, v19
	v_add_f32_e32 v7, v11, v7
	v_add_f32_e32 v11, v21, v7
	v_mul_f32_e32 v17, v18, v11
	v_mul_f32_e32 v19, v6, v17
	v_fma_f32 v6, v17, v6, -v19
	v_fmac_f32_e32 v6, v17, v2
	v_sub_f32_e32 v2, v21, v11
	v_add_f32_e32 v2, v7, v2
	v_add_f32_e32 v7, v19, v6
	v_sub_f32_e32 v20, v11, v7
	v_sub_f32_e32 v11, v11, v20
	v_sub_f32_e32 v19, v7, v19
	v_sub_f32_e32 v7, v11, v7
	v_add_f32_e32 v2, v2, v7
	v_sub_f32_e32 v6, v19, v6
	v_add_f32_e32 v2, v6, v2
	v_add_f32_e32 v22, v10, v17
	v_add_f32_e32 v2, v20, v2
	v_sub_f32_e32 v6, v22, v10
	v_mul_f32_e32 v2, v18, v2
	v_sub_f32_e32 v6, v17, v6
	v_add_f32_e32 v23, v6, v2
	v_lshlrev_b32_e32 v2, 3, v58
	v_and_b32_e32 v27, 56, v2
	v_lshlrev_b32_e32 v2, 7, v8
	v_lshl_add_u64 v[6:7], s[22:23], 0, v[2:3]
	v_lshlrev_b32_e32 v2, 1, v27
	v_lshlrev_b32_e32 v17, 7, v13
	v_lshl_add_u64 v[6:7], v[6:7], 0, v[2:3]
	v_bfe_u32 v2, v58, 3, 5
	v_or_b32_e32 v10, v2, v17
	v_mad_i64_i32 v[10:11], s[2:3], v10, s54, v[6:7]
	s_waitcnt vmcnt(7)
	v_mov_b32_e32 v18, v200
	v_mov_b32_e32 v19, v201
	v_mov_b32_e32 v20, v202
	v_mov_b32_e32 v21, v203
	v_cvt_f32_i32_e32 v14, v14
	v_add_f32_e32 v24, v22, v23
	v_mul_f32_e32 v25, v24, v24
	v_fmamk_f32 v28, v25, 0x3e9b6dac, v47
	v_mul_f32_e32 v29, 0x3f317218, v14
	v_fma_f32 v30, v14, s52, -v29
	v_fmac_f32_e32 v30, 0xb102e308, v14
	v_sub_f32_e32 v14, v24, v22
	v_add_f32_e32 v31, v29, v30
	v_fmaak_f32 v28, v25, v28, 0x3f2aaada
	v_sub_f32_e32 v14, v23, v14
	v_sub_f32_e32 v22, v31, v29
	v_mul_f32_e32 v23, v24, v25
	v_sub_f32_e32 v29, v30, v22
	v_ldexp_f32 v22, v24, 1
	v_mul_f32_e32 v23, v23, v28
	v_add_f32_e32 v24, v22, v23
	v_sub_f32_e32 v22, v24, v22
	v_ldexp_f32 v14, v14, 1
	v_sub_f32_e32 v22, v23, v22
	v_add_f32_e32 v14, v14, v22
	v_add_f32_e32 v28, v24, v14
	v_sub_f32_e32 v22, v28, v24
	v_sub_f32_e32 v14, v14, v22
	s_waitcnt vmcnt(6)
	v_mov_b32_e32 v22, v204
	v_mov_b32_e32 v23, v205
	v_mov_b32_e32 v24, v206
	v_mov_b32_e32 v25, v207
	v_add_f32_e32 v30, v31, v28
	v_sub_f32_e32 v32, v30, v31
	v_sub_f32_e32 v33, v30, v32
	v_sub_f32_e32 v10, v31, v33
	v_sub_f32_e32 v11, v28, v32
	v_add_f32_e32 v10, v11, v10
	v_add_f32_e32 v11, v29, v14
	v_sub_f32_e32 v28, v11, v29
	v_add_f32_e32 v10, v11, v10
	v_sub_f32_e32 v31, v11, v28
	v_add_f32_e32 v11, v30, v10
	v_sub_f32_e32 v29, v29, v31
	v_sub_f32_e32 v14, v14, v28
	v_sub_f32_e32 v28, v11, v30
	v_add_f32_e32 v14, v14, v29
	v_sub_f32_e32 v10, v10, v28
	v_add_f32_e32 v10, v14, v10
	v_add_f32_e32 v10, v11, v10
	v_xor_b32_e32 v11, 0x7f, v2
	v_cvt_f32_ubyte0_e32 v11, v11
	v_mul_f32_e64 v11, v11, -v9
	v_mul_f32_e32 v14, 0x3fb8aa3b, v11
	v_fma_f32 v28, v11, s55, -v14
	v_rndne_f32_e32 v29, v14
	v_fmac_f32_e32 v28, 0x32a5705f, v11
	v_sub_f32_e32 v14, v14, v29
	v_add_f32_e32 v14, v14, v28
	v_exp_f32_e32 v14, v14
	v_cvt_i32_f32_e32 v28, v29
	v_cmp_neq_f32_e32 vcc, s50, v15
	v_or_b32_e32 v38, 32, v2
	v_mul_u32_u24_e32 v27, 0x88, v27
	v_cndmask_b32_e32 v10, v46, v10, vcc
	v_cmp_lt_f32_e64 vcc, |v15|, s53
	v_lshlrev_b32_e32 v27, 1, v27
	v_lshlrev_b32_e32 v33, 16, v20
	v_cndmask_b32_e32 v15, v10, v15, vcc
	v_ldexp_f32 v10, v14, v28
	v_cvt_f32_ubyte0_e32 v14, v2
	v_mul_f32_e64 v14, v14, -v15
	v_mul_f32_e32 v28, 0x3fb8aa3b, v14
	v_fma_f32 v29, v14, s55, -v28
	v_rndne_f32_e32 v30, v28
	v_fmac_f32_e32 v29, 0x32a5705f, v14
	v_sub_f32_e32 v28, v28, v30
	v_add_f32_e32 v28, v28, v29
	v_exp_f32_e32 v28, v28
	v_cvt_i32_f32_e32 v29, v30
	v_cmp_ngt_f32_e32 vcc, s56, v11
	v_and_b32_e32 v34, 0xffff0000, v20
	v_lshlrev_b32_e32 v35, 16, v21
	v_cndmask_b32_e32 v10, 0, v10, vcc
	v_cmp_nlt_f32_e32 vcc, s57, v11
	v_and_b32_e32 v11, 0xffff0000, v18
	v_and_b32_e32 v36, 0xffff0000, v21
	v_cndmask_b32_e32 v10, v46, v10, vcc
	v_mul_f32_e32 v32, 0x3e000000, v10
	v_ldexp_f32 v10, v28, v29
	v_cmp_ngt_f32_e32 vcc, s56, v14
	v_lshlrev_b32_e32 v28, 16, v19
	v_and_b32_e32 v29, 0xffff0000, v19
	v_cndmask_b32_e32 v10, 0, v10, vcc
	v_cmp_nlt_f32_e32 vcc, s57, v14
	v_mul_f32_e32 v19, v32, v11
	v_lshlrev_b32_e32 v30, 1, v2
	v_cndmask_b32_e32 v10, v46, v10, vcc
	v_mul_f32_e32 v14, 0x3e000000, v10
	v_lshlrev_b32_e32 v10, 16, v18
	v_mul_f32_e32 v18, v32, v10
	v_mul_f32_e32 v10, v14, v10
	v_mul_f32_e32 v11, v14, v11
	v_cvt_pk_bf16_f32 v37, v10, v11
	v_or_b32_e32 v10, v38, v17
	v_mad_i64_i32 v[10:11], s[2:3], v10, s54, v[6:7]
	v_cvt_pk_bf16_f32 v31, v18, v19
	s_waitcnt vmcnt(5)
	v_mov_b32_e32 v18, v208
	v_mov_b32_e32 v19, v209
	v_mov_b32_e32 v20, v210
	v_mov_b32_e32 v21, v211
	v_add3_u32 v27, v44, v30, v27
	ds_write_b16 v27, v31
	ds_write_b16_d16_hi v27, v31 offset:272
	ds_write_b16 v27, v37 offset:17408
	ds_write_b16_d16_hi v27, v37 offset:17680
	ds_write_b16 v27, v22 offset:34816
	ds_write_b16_d16_hi v27, v22 offset:35088
	v_mul_f32_e32 v22, v32, v28
	v_mul_f32_e32 v30, v32, v29
	v_cvt_pk_bf16_f32 v22, v22, v30
	v_mul_f32_e32 v28, v14, v28
	v_mul_f32_e32 v29, v14, v29
	v_cvt_pk_bf16_f32 v28, v28, v29
	ds_write_b16 v27, v22 offset:544
	ds_write_b16_d16_hi v27, v22 offset:816
	ds_write_b16 v27, v28 offset:17952
	ds_write_b16_d16_hi v27, v28 offset:18224
	ds_write_b16 v27, v23 offset:35360
	ds_write_b16_d16_hi v27, v23 offset:35632
	s_waitcnt vmcnt(4)
	v_mov_b32_e32 v28, v212
	v_mov_b32_e32 v29, v213
	v_mov_b32_e32 v30, v214
	v_mov_b32_e32 v31, v215
	v_mul_f32_e32 v22, v32, v33
	v_mul_f32_e32 v10, v32, v34
	v_mul_f32_e32 v11, v14, v33
	v_cvt_pk_bf16_f32 v10, v22, v10
	v_mul_f32_e32 v22, v14, v34
	v_cvt_pk_bf16_f32 v11, v11, v22
	ds_write_b16 v27, v10 offset:1088
	ds_write_b16_d16_hi v27, v10 offset:1360
	ds_write_b16 v27, v11 offset:18496
	ds_write_b16_d16_hi v27, v11 offset:18768
	ds_write_b16 v27, v24 offset:35904
	ds_write_b16_d16_hi v27, v24 offset:36176
	v_mul_f32_e32 v10, v32, v35
	v_mul_f32_e32 v11, v32, v36
	v_cvt_pk_bf16_f32 v10, v10, v11
	v_mul_f32_e32 v11, v14, v35
	v_mul_f32_e32 v14, v14, v36
	v_cvt_pk_bf16_f32 v11, v11, v14
	ds_write_b16 v27, v10 offset:1632
	ds_write_b16_d16_hi v27, v10 offset:1904
	ds_write_b16 v27, v11 offset:19040
	v_xor_b32_e32 v10, 0x5f, v2
	v_cvt_f32_ubyte0_e32 v10, v10
	v_mul_f32_e64 v10, v10, -v9
	v_mul_f32_e32 v14, 0x3fb8aa3b, v10
	v_fma_f32 v22, v10, s55, -v14
	v_rndne_f32_e32 v23, v14
	v_fmac_f32_e32 v22, 0x32a5705f, v10
	v_sub_f32_e32 v14, v14, v23
	v_add_f32_e32 v14, v14, v22
	v_exp_f32_e32 v14, v14
	v_cvt_i32_f32_e32 v22, v23
	ds_write_b16_d16_hi v27, v11 offset:19312
	ds_write_b16 v27, v25 offset:36448
	ds_write_b16_d16_hi v27, v25 offset:36720
	v_cmp_ngt_f32_e32 vcc, s56, v10
	v_ldexp_f32 v11, v14, v22
	v_cvt_f32_ubyte0_e32 v14, v38
	v_mul_f32_e64 v14, v14, -v15
	v_mul_f32_e32 v22, 0x3fb8aa3b, v14
	v_fma_f32 v23, v14, s55, -v22
	v_rndne_f32_e32 v24, v22
	v_fmac_f32_e32 v23, 0x32a5705f, v14
	v_sub_f32_e32 v22, v22, v24
	v_add_f32_e32 v22, v22, v23
	v_exp_f32_e32 v22, v22
	v_cvt_i32_f32_e32 v23, v24
	v_cndmask_b32_e32 v11, 0, v11, vcc
	v_cmp_nlt_f32_e32 vcc, s57, v10
	v_or_b32_e32 v38, 64, v2
	v_lshlrev_b32_e32 v24, 16, v19
	v_cndmask_b32_e32 v10, v46, v11, vcc
	v_mul_f32_e32 v32, 0x3e000000, v10
	v_ldexp_f32 v10, v22, v23
	v_cmp_ngt_f32_e32 vcc, s56, v14
	v_lshlrev_b32_e32 v22, 16, v18
	v_and_b32_e32 v23, 0xffff0000, v18
	v_cndmask_b32_e32 v10, 0, v10, vcc
	v_cmp_nlt_f32_e32 vcc, s57, v14
	v_mul_f32_e32 v11, v32, v23
	v_and_b32_e32 v25, 0xffff0000, v19
	v_cndmask_b32_e32 v10, v46, v10, vcc
	v_mul_f32_e32 v14, 0x3e000000, v10
	v_mul_f32_e32 v10, v32, v22
	v_cvt_pk_bf16_f32 v37, v10, v11
	v_or_b32_e32 v10, v38, v17
	v_mad_i64_i32 v[10:11], s[2:3], v10, s54, v[6:7]
	v_lshlrev_b32_e32 v33, 16, v20
	v_and_b32_e32 v34, 0xffff0000, v20
	v_lshlrev_b32_e32 v35, 16, v21
	v_and_b32_e32 v36, 0xffff0000, v21
	s_waitcnt vmcnt(3)
	v_mov_b32_e32 v18, v216
	v_mov_b32_e32 v19, v217
	v_mov_b32_e32 v20, v218
	v_mov_b32_e32 v21, v219
	v_mul_f32_e32 v22, v14, v22
	v_mul_f32_e32 v23, v14, v23
	v_cvt_pk_bf16_f32 v22, v22, v23
	ds_write_b16 v27, v37 offset:64
	ds_write_b16_d16_hi v27, v37 offset:336
	ds_write_b16 v27, v22 offset:17472
	ds_write_b16_d16_hi v27, v22 offset:17744
	ds_write_b16 v27, v28 offset:34880
	ds_write_b16_d16_hi v27, v28 offset:35152
	v_mul_f32_e32 v22, v32, v24
	v_mul_f32_e32 v23, v32, v25
	v_cvt_pk_bf16_f32 v22, v22, v23
	v_mul_f32_e32 v23, v14, v24
	v_mul_f32_e32 v24, v14, v25
	v_cvt_pk_bf16_f32 v23, v23, v24
	ds_write_b16 v27, v22 offset:608
	ds_write_b16_d16_hi v27, v22 offset:880
	ds_write_b16 v27, v23 offset:18016
	ds_write_b16_d16_hi v27, v23 offset:18288
	ds_write_b16 v27, v29 offset:35424
	ds_write_b16_d16_hi v27, v29 offset:35696
	s_waitcnt vmcnt(2)
	v_mov_b32_e32 v22, v220
	v_mov_b32_e32 v23, v221
	v_mov_b32_e32 v24, v222
	v_mov_b32_e32 v25, v223
	v_mul_f32_e32 v28, v32, v33
	v_mul_f32_e32 v10, v32, v34
	v_mul_f32_e32 v11, v14, v33
	v_cvt_pk_bf16_f32 v10, v28, v10
	v_mul_f32_e32 v28, v14, v34
	v_cvt_pk_bf16_f32 v11, v11, v28
	ds_write_b16 v27, v10 offset:1152
	ds_write_b16_d16_hi v27, v10 offset:1424
	ds_write_b16 v27, v11 offset:18560
	ds_write_b16_d16_hi v27, v11 offset:18832
	ds_write_b16 v27, v30 offset:35968
	ds_write_b16_d16_hi v27, v30 offset:36240
	v_mul_f32_e32 v10, v32, v35
	v_mul_f32_e32 v11, v32, v36
	v_cvt_pk_bf16_f32 v10, v10, v11
	v_mul_f32_e32 v11, v14, v35
	v_mul_f32_e32 v14, v14, v36
	v_cvt_pk_bf16_f32 v11, v11, v14
	ds_write_b16 v27, v10 offset:1696
	ds_write_b16_d16_hi v27, v10 offset:1968
	ds_write_b16 v27, v11 offset:19104
	v_xor_b32_e32 v10, 63, v2
	v_cvt_f32_ubyte0_e32 v10, v10
	v_mul_f32_e64 v10, v10, -v9
	v_mul_f32_e32 v14, 0x3fb8aa3b, v10
	v_fma_f32 v28, v10, s55, -v14
	v_rndne_f32_e32 v29, v14
	v_fmac_f32_e32 v28, 0x32a5705f, v10
	v_sub_f32_e32 v14, v14, v29
	v_add_f32_e32 v14, v14, v28
	v_exp_f32_e32 v14, v14
	v_cvt_i32_f32_e32 v28, v29
	ds_write_b16_d16_hi v27, v11 offset:19376
	ds_write_b16 v27, v31 offset:36512
	ds_write_b16_d16_hi v27, v31 offset:36784
	v_cmp_ngt_f32_e32 vcc, s56, v10
	v_or_b32_e32 v36, 0x60, v2
	v_ldexp_f32 v11, v14, v28
	v_cvt_f32_ubyte0_e32 v14, v38
	v_mul_f32_e64 v14, v14, -v15
	v_mul_f32_e32 v28, 0x3fb8aa3b, v14
	v_fma_f32 v29, v14, s55, -v28
	v_rndne_f32_e32 v30, v28
	v_fmac_f32_e32 v29, 0x32a5705f, v14
	v_sub_f32_e32 v28, v28, v30
	v_add_f32_e32 v28, v28, v29
	v_exp_f32_e32 v28, v28
	v_cvt_i32_f32_e32 v29, v30
	v_cndmask_b32_e32 v11, 0, v11, vcc
	v_cmp_nlt_f32_e32 vcc, s57, v10
	v_xor_b32_e32 v2, 31, v2
	v_cvt_f32_ubyte0_e32 v2, v2
	v_cndmask_b32_e32 v10, v46, v11, vcc
	v_ldexp_f32 v11, v28, v29
	v_cmp_ngt_f32_e32 vcc, s56, v14
	v_mul_f32_e32 v10, 0x3e000000, v10
	v_mul_f32_e64 v2, v2, -v9
	v_cndmask_b32_e32 v11, 0, v11, vcc
	v_cmp_nlt_f32_e32 vcc, s57, v14
	v_lshlrev_b32_e32 v14, 16, v18
	v_and_b32_e32 v28, 0xffff0000, v18
	v_mul_f32_e32 v18, v10, v14
	v_lshlrev_b32_e32 v29, 16, v19
	v_and_b32_e32 v30, 0xffff0000, v19
	v_mul_f32_e32 v19, v10, v28
	v_cvt_pk_bf16_f32 v31, v18, v19
	v_or_b32_e32 v18, v36, v17
	v_mad_i64_i32 v[6:7], s[2:3], v18, s54, v[6:7]
	v_cndmask_b32_e32 v11, v46, v11, vcc
	v_lshlrev_b32_e32 v32, 16, v20
	v_and_b32_e32 v33, 0xffff0000, v20
	v_lshlrev_b32_e32 v34, 16, v21
	v_and_b32_e32 v35, 0xffff0000, v21
	s_waitcnt vmcnt(1)
	v_mov_b32_e32 v18, v224
	v_mov_b32_e32 v19, v225
	v_mov_b32_e32 v20, v226
	v_mov_b32_e32 v21, v227
	v_mul_f32_e32 v11, 0x3e000000, v11
	v_mul_f32_e32 v14, v11, v14
	v_mul_f32_e32 v28, v11, v28
	v_cvt_pk_bf16_f32 v14, v14, v28
	ds_write_b16 v27, v31 offset:128
	ds_write_b16_d16_hi v27, v31 offset:400
	ds_write_b16 v27, v14 offset:17536
	ds_write_b16_d16_hi v27, v14 offset:17808
	ds_write_b16 v27, v22 offset:34944
	ds_write_b16_d16_hi v27, v22 offset:35216
	v_mul_f32_e32 v14, v10, v29
	v_mul_f32_e32 v22, v10, v30
	v_cvt_pk_bf16_f32 v14, v14, v22
	v_mul_f32_e32 v22, v11, v29
	v_mul_f32_e32 v28, v11, v30
	ds_write_b16 v27, v14 offset:672
	ds_write_b16_d16_hi v27, v14 offset:944
	v_cvt_pk_bf16_f32 v22, v22, v28
	s_waitcnt vmcnt(0)
	v_mov_b32_e32 v28, v228
	v_mov_b32_e32 v29, v229
	v_mov_b32_e32 v30, v230
	v_mov_b32_e32 v31, v231
	v_mul_f32_e32 v6, v10, v32
	v_mul_f32_e32 v7, v10, v33
	v_cvt_pk_bf16_f32 v6, v6, v7
	v_mul_f32_e32 v7, v11, v32
	v_mul_f32_e32 v14, v11, v33
	v_cvt_pk_bf16_f32 v7, v7, v14
	ds_write_b16 v27, v22 offset:18080
	ds_write_b16_d16_hi v27, v22 offset:18352
	ds_write_b16 v27, v23 offset:35488
	ds_write_b16_d16_hi v27, v23 offset:35760
	ds_write_b16 v27, v6 offset:1216
	ds_write_b16_d16_hi v27, v6 offset:1488
	ds_write_b16 v27, v7 offset:18624
	ds_write_b16_d16_hi v27, v7 offset:18896
	ds_write_b16 v27, v24 offset:36032
	ds_write_b16_d16_hi v27, v24 offset:36304
	v_mul_f32_e32 v6, v10, v34
	v_mul_f32_e32 v7, v10, v35
	v_cvt_pk_bf16_f32 v6, v6, v7
	v_mul_f32_e32 v7, v11, v34
	v_mul_f32_e32 v10, v11, v35
	v_cvt_pk_bf16_f32 v7, v7, v10
	ds_write_b16 v27, v6 offset:1760
	ds_write_b16_d16_hi v27, v6 offset:2032
	ds_write_b16 v27, v7 offset:19168
	v_mul_f32_e32 v6, 0x3fb8aa3b, v2
	v_fma_f32 v9, v2, s55, -v6
	v_rndne_f32_e32 v10, v6
	v_fmac_f32_e32 v9, 0x32a5705f, v2
	v_sub_f32_e32 v6, v6, v10
	v_add_f32_e32 v6, v6, v9
	v_exp_f32_e32 v6, v6
	v_cvt_i32_f32_e32 v9, v10
	ds_write_b16_d16_hi v27, v7 offset:19440
	ds_write_b16 v27, v25 offset:36576
	ds_write_b16_d16_hi v27, v25 offset:36848
	v_cvt_f32_ubyte0_e32 v7, v36
	v_mul_f32_e64 v7, v7, -v15
	v_ldexp_f32 v6, v6, v9
	v_mul_f32_e32 v9, 0x3fb8aa3b, v7
	v_fma_f32 v10, v7, s55, -v9
	v_rndne_f32_e32 v11, v9
	v_fmac_f32_e32 v10, 0x32a5705f, v7
	v_sub_f32_e32 v9, v9, v11
	v_add_f32_e32 v9, v9, v10
	v_exp_f32_e32 v9, v9
	v_cvt_i32_f32_e32 v10, v11
	v_cmp_ngt_f32_e32 vcc, s56, v2
	v_cmp_eq_u32_e64 s[2:3], 0, v26
	v_lshlrev_b32_e32 v14, 16, v20
	v_cndmask_b32_e32 v6, 0, v6, vcc
	v_cmp_nlt_f32_e32 vcc, s57, v2
	v_and_b32_e32 v15, 0xffff0000, v20
	v_and_b32_e32 v11, 0xffff0000, v19
	v_cndmask_b32_e32 v2, v46, v6, vcc
	v_ldexp_f32 v6, v9, v10
	v_cmp_ngt_f32_e32 vcc, s56, v7
	v_mul_f32_e32 v2, 0x3e000000, v2
	v_and_b32_e32 v9, 0xffff0000, v18
	v_cndmask_b32_e32 v6, 0, v6, vcc
	v_cmp_nlt_f32_e32 vcc, s57, v7
	v_lshlrev_b32_e32 v7, 16, v18
	v_mul_f32_e32 v20, v2, v7
	v_cndmask_b32_e32 v6, v46, v6, vcc
	v_mul_f32_e32 v6, 0x3e000000, v6
	v_mul_f32_e32 v7, v6, v7
	v_lshlrev_b32_e32 v10, 16, v19
	v_lshlrev_b32_e32 v18, 16, v21
	v_and_b32_e32 v19, 0xffff0000, v21
	v_mul_f32_e32 v21, v2, v9
	v_cvt_pk_bf16_f32 v20, v20, v21
	v_mul_f32_e32 v9, v6, v9
	v_cvt_pk_bf16_f32 v7, v7, v9
	ds_write_b16 v27, v20 offset:192
	ds_write_b16_d16_hi v27, v20 offset:464
	ds_write_b16 v27, v7 offset:17600
	ds_write_b16_d16_hi v27, v7 offset:17872
	ds_write_b16 v27, v28 offset:35008
	ds_write_b16_d16_hi v27, v28 offset:35280
	v_mul_f32_e32 v7, v2, v10
	v_mul_f32_e32 v9, v2, v11
	v_cvt_pk_bf16_f32 v7, v7, v9
	v_mul_f32_e32 v9, v6, v10
	v_mul_f32_e32 v10, v6, v11
	v_cvt_pk_bf16_f32 v9, v9, v10
	ds_write_b16 v27, v7 offset:736
	ds_write_b16_d16_hi v27, v7 offset:1008
	ds_write_b16 v27, v9 offset:18144
	ds_write_b16_d16_hi v27, v9 offset:18416
	ds_write_b16 v27, v29 offset:35552
	ds_write_b16_d16_hi v27, v29 offset:35824
	v_mul_f32_e32 v7, v2, v14
	v_mul_f32_e32 v9, v2, v15
	v_cvt_pk_bf16_f32 v7, v7, v9
	v_mul_f32_e32 v9, v6, v14
	v_mul_f32_e32 v10, v6, v15
	v_cvt_pk_bf16_f32 v9, v9, v10
	ds_write_b16 v27, v7 offset:1280
	ds_write_b16_d16_hi v27, v7 offset:1552
	ds_write_b16 v27, v9 offset:18688
	ds_write_b16_d16_hi v27, v9 offset:18960
	ds_write_b16 v27, v30 offset:36096
	ds_write_b16_d16_hi v27, v30 offset:36368
	v_mul_f32_e32 v7, v2, v18
	v_mul_f32_e32 v2, v2, v19
	v_cvt_pk_bf16_f32 v2, v7, v2
	v_mul_f32_e32 v7, v6, v18
	v_mul_f32_e32 v6, v6, v19
	v_cvt_pk_bf16_f32 v6, v7, v6
	v_lshlrev_b32_e32 v14, 5, v8
	v_lshlrev_b32_e32 v18, 3, v59
	v_cmp_lt_i32_e32 vcc, v51, v50
	ds_write_b16 v27, v2 offset:1824
	ds_write_b16_d16_hi v27, v2 offset:2096
	ds_write_b16 v27, v6 offset:19232
	ds_write_b16_d16_hi v27, v6 offset:19504
	ds_write_b16 v27, v31 offset:36640
	ds_write_b16_d16_hi v27, v31 offset:36912
	v_cndmask_b32_e32 v6, v49, v51, vcc
	v_cmp_lt_i32_e32 vcc, v52, v50
	v_lshlrev_b32_e32 v15, 8, v13
	v_or3_b32 v67, v14, v18, v17
	v_lshlrev_b16_e32 v13, 7, v13
	v_lshlrev_b16_e32 v14, 3, v59
	v_lshlrev_b32_e32 v60, 2, v6
	v_cndmask_b32_e32 v6, v49, v52, vcc
	v_cmp_lt_i32_e32 vcc, v53, v50
	v_bitop3_b16 v12, v13, v12, v14 bitop3:0xfe
	v_lshlrev_b32_e32 v61, 2, v6
	v_cndmask_b32_e32 v6, v49, v53, vcc
	v_cmp_lt_i32_e32 vcc, v54, v50
	v_and_b32_e32 v68, 0x7f8, v12
	v_and_b32_e32 v12, 0xf8, v12
	v_lshlrev_b32_e32 v62, 2, v6
	v_cndmask_b32_e32 v6, v49, v54, vcc
	v_cmp_lt_i32_e32 vcc, v55, v50
	v_and_or_b32 v14, v15, s58, v12
	v_lshlrev_b32_e32 v63, 2, v6
	v_cndmask_b32_e32 v6, v49, v55, vcc
	v_cmp_lt_i32_e32 vcc, v56, v50
	v_lshlrev_b32_e32 v10, 4, v26
	v_mov_b32_e32 v11, v3
	v_ashrrev_i32_e32 v15, 31, v14
	v_or3_b32 v16, v17, v16, v18
	v_lshlrev_b32_e32 v2, 2, v26
	v_lshlrev_b32_e32 v64, 2, v6
	v_cndmask_b32_e32 v6, v49, v56, vcc
	v_lshlrev_b32_e32 v28, 3, v26
	v_mov_b32_e32 v29, v3
	v_add_u32_e32 v8, 0xffffe000, v17
	s_waitcnt lgkmcnt(0)
	v_lshl_add_u64 v[10:11], s[6:7], 0, v[10:11]
	v_lshlrev_b64 v[12:13], 7, v[14:15]
	v_lshlrev_b64 v[14:15], 9, v[14:15]
	v_ashrrev_i32_e32 v17, 31, v16
	v_mad_i64_i32 v[22:23], s[6:7], v16, s54, 0
	v_lshlrev_b32_e32 v65, 2, v6
	v_lshl_add_u64 v[6:7], s[4:5], 0, v[28:29]
	v_lshrrev_b32_e32 v8, 3, v8
	v_cmp_gt_u32_e64 s[4:5], 32, v26
	v_or_b32_e32 v12, v12, v2
	v_or_b32_e32 v14, v14, v28
	v_lshlrev_b64 v[20:21], 11, v[16:17]
	v_or_b32_e32 v24, v22, v2
	v_mov_b32_e32 v25, v23
	v_lshl_or_b32 v26, v26, 1, v22
	v_mov_b32_e32 v27, v23
	v_and_b32_e32 v66, 0x1fffff00, v8
	v_lshl_add_u64 v[8:9], s[24:25], 0, v[2:3]
	v_lshl_add_u64 v[12:13], s[28:29], 0, v[12:13]
	v_lshl_add_u64 v[14:15], s[12:13], 0, v[14:15]
	v_lshl_add_u64 v[18:19], v[16:17], 2, v[4:5]
	v_or_b32_e32 v20, v20, v28
	v_lshl_add_u64 v[24:25], v[24:25], 0, s[34:35]
	v_lshl_add_u64 v[26:27], v[26:27], 0, s[36:37]
	v_or_b32_e32 v22, v22, v28
	s_branch .LBB0_423

.LBB0_624:
	v_lshlrev_b32_e32 v162, 4, v149
	v_mul_f32_e32 v167, v127, v127
	v_fmac_f32_e32 v167, v126, v126
	v_fmac_f32_e32 v167, v128, v128
	v_fmac_f32_e32 v167, v129, v129
	v_fmac_f32_e32 v167, v122, v122
	v_fmac_f32_e32 v167, v123, v123
	v_fmac_f32_e32 v167, v124, v124
	v_fmac_f32_e32 v167, v125, v125
	v_fmac_f32_e32 v167, v118, v118
	v_fmac_f32_e32 v167, v119, v119
	v_fmac_f32_e32 v167, v120, v120
	v_fmac_f32_e32 v167, v121, v121
	v_fmac_f32_e32 v167, v114, v114
	v_fmac_f32_e32 v167, v115, v115
	v_fmac_f32_e32 v167, v116, v116
	s_waitcnt vmcnt(14)
	v_pk_mul_f32 v[140:141], v[130:131], v[130:131]
	v_fmac_f32_e32 v167, v117, v117
	v_add_f32_e32 v140, v167, v140
	v_pk_mul_f32 v[144:145], v[132:133], v[132:133]
	v_add_f32_e32 v140, v141, v140
	v_add_f32_e32 v140, v144, v140
	v_and_b32_e32 v146, 64, v166
	v_pk_mul_f32 v[156:157], v[134:135], v[134:135]
	v_add_f32_e32 v140, v145, v140
	v_xor_b32_e32 v143, 16, v166
	v_add_u32_e32 v168, 64, v146
	v_add_f32_e32 v140, v156, v140
	v_pk_mul_f32 v[158:159], v[136:137], v[136:137]
	v_cmp_lt_i32_e32 vcc, v143, v168
	v_add_f32_e32 v140, v157, v140
	v_add_f32_e32 v140, v158, v140
	v_cndmask_b32_e32 v143, v166, v143, vcc
	v_lshlrev_b32_e32 v146, 2, v143
	v_add_f32_e32 v140, v159, v140
	v_mov_b32_e32 v141, v140
	s_nop 1
	v_permlane16_swap_b32_e32 v141, v140
	v_xor_b32_e32 v148, 32, v166
	v_cmp_lt_i32_e32 vcc, v148, v168
	v_lshrrev_b32_e32 v151, 6, v150
	s_lshl_b32 s2, s58, 2
	v_cndmask_b32_e32 v144, v166, v148, vcc
	v_lshlrev_b32_e32 v148, 2, v144
	s_waitcnt lgkmcnt(0)
	v_add_f32_e32 v141, v140, v141
	v_mov_b32_e32 v156, v141
	s_nop 1
	v_permlane32_swap_b32_e32 v156, v141
	v_mov_b64_e32 v[160:161], s[24:25]
	v_and_or_b32 v140, v151, 3, s2
	v_mad_i64_i32 v[144:145], s[2:3], v139, s57, v[160:161]
	s_waitcnt lgkmcnt(0)
	v_add_f32_e32 v139, v141, v156
	v_fmamk_f32 v139, v139, 0x3c2aaaab, v1
	v_mul_f32_e32 v141, 0x4b800000, v139
	v_cmp_gt_f32_e32 vcc, s56, v139
	v_mul_lo_u32 v140, v140, s55
	v_mov_b32_e32 v143, v163
	v_cndmask_b32_e32 v139, v139, v141, vcc
	v_rsq_f32_e32 v139, v139
	v_ashrrev_i32_e32 v141, 31, v140
	v_lshl_add_u64 v[144:145], v[140:141], 1, v[144:145]
	v_lshl_add_u64 v[156:157], v[144:145], 0, v[142:143]
	v_mul_f32_e32 v143, 0x45800000, v139
	v_cndmask_b32_e32 v158, v139, v143, vcc
	v_mul_f32_e32 v126, v126, v158
	v_mul_f32_e32 v127, v127, v158
	v_mul_f32_e32 v128, v128, v158
	v_mul_f32_e32 v129, v129, v158
	v_mul_f32_e32 v122, v122, v158
	v_mul_f32_e32 v123, v123, v158
	v_mul_f32_e32 v124, v124, v158
	v_mul_f32_e32 v125, v125, v158
	v_mul_f32_e32 v118, v118, v158
	v_mul_f32_e32 v119, v119, v158
	v_mul_f32_e32 v120, v120, v158
	v_mul_f32_e32 v121, v121, v158
	v_mul_f32_e32 v114, v114, v158
	v_mul_f32_e32 v115, v115, v158
	v_mul_f32_e32 v116, v116, v158
	v_mul_f32_e32 v117, v117, v158
	s_cmp_eq_u32 s62, 1
	v_cmp_gt_u32_e64 s[4:5], 2, v149
	s_cselect_b64 s[30:31], -1, 0
	v_mul_f32_e32 v126, v170, v126
	v_mul_f32_e32 v127, v171, v127
	v_mul_f32_e32 v128, v172, v128
	v_mul_f32_e32 v129, v173, v129
	v_cvt_pk_bf16_f32 v126, v126, v127
	v_cvt_pk_bf16_f32 v127, v128, v129
	global_store_dwordx2 v[156:157], v[126:127], off
	s_cmp_lg_u32 s62, 1
	v_mul_f32_e32 v122, v174, v122
	v_mul_f32_e32 v123, v175, v123
	v_mul_f32_e32 v124, v176, v124
	v_mul_f32_e32 v125, v177, v125
	v_cvt_pk_bf16_f32 v122, v122, v123
	v_cvt_pk_bf16_f32 v123, v124, v125
	global_store_dwordx2 v[156:157], v[122:123], off offset:32
	v_mul_f32_e32 v118, v178, v118
	v_mul_f32_e32 v119, v179, v119
	v_mul_f32_e32 v120, v180, v120
	v_mul_f32_e32 v121, v121, v181
	v_cvt_pk_bf16_f32 v118, v118, v119
	v_cvt_pk_bf16_f32 v119, v120, v121
	global_store_dwordx2 v[156:157], v[118:119], off offset:64
	v_and_b32_e32 v122, 16, v150
	v_cmp_eq_u32_e64 s[2:3], 0, v122
	v_mul_f32_e32 v114, v114, v182
	v_mul_f32_e32 v115, v115, v183
	v_mul_f32_e32 v116, v116, v184
	v_mul_f32_e32 v117, v117, v185
	v_cvt_pk_bf16_f32 v114, v114, v115
	v_cvt_pk_bf16_f32 v115, v116, v117
	global_store_dwordx2 v[156:157], v[114:115], off offset:96
	s_nop 0
	v_mov_b32_e32 v114, v186
	v_mov_b32_e32 v115, v187
	v_mov_b32_e32 v116, v188
	v_mov_b32_e32 v117, v189
	v_pk_mul_f32 v[114:115], v[158:159], v[114:115] op_sel_hi:[0,1]
	v_pk_mul_f32 v[116:117], v[158:159], v[116:117] op_sel_hi:[0,1]
	v_pk_mul_f32 v[122:123], v[158:159], v[190:191] op_sel_hi:[0,1]
	v_pk_mul_f32 v[124:125], v[158:159], v[192:193] op_sel_hi:[0,1]
	v_pk_mul_f32 v[120:121], v[130:131], v[114:115]
	v_pk_mul_f32 v[118:119], v[132:133], v[116:117]
	v_pk_mul_f32 v[116:117], v[134:135], v[122:123]
	v_pk_mul_f32 v[114:115], v[136:137], v[124:125]
	s_cbranch_scc1 .LBB0_626
	v_add_u32_e32 v122, s60, v147
	v_ashrrev_i32_e32 v123, 6, v122
	v_and_b32_e32 v122, 63, v122
	v_cndmask_b32_e64 v122, v122, v123, s[4:5]
	v_cvt_f32_i32_e32 v130, v122
	ds_bpermute_b32 v122, v146, v120
	ds_bpermute_b32 v123, v146, v121
	v_mul_f32_e32 v125, 0x3ea1e89b, v130
	v_mul_f32_e32 v126, 0.15915494, v130
	v_mul_f32_e32 v127, 0.15915494, v125
	v_sin_f32_e32 v124, v126
	v_sin_f32_e32 v125, v127
	v_mul_f32_e32 v129, 0x3d0186e3, v130
	v_mul_f32_e32 v132, 0.15915494, v129
	v_cos_f32_e32 v126, v126
	s_waitcnt lgkmcnt(0)
	v_pk_mul_f32 v[122:123], v[124:125], v[122:123]
	v_mul_f32_e32 v125, 0x3dcccccd, v130
	ds_bpermute_b32 v124, v146, v118
	v_mul_f32_e32 v131, 0.15915494, v125
	ds_bpermute_b32 v125, v146, v119
	v_cos_f32_e32 v127, v127
	v_sin_f32_e32 v128, v131
	v_sin_f32_e32 v129, v132
	v_cndmask_b32_e64 v123, v123, -v123, s[2:3]
	v_cndmask_b32_e64 v122, v122, -v122, s[2:3]
	v_pk_fma_f32 v[120:121], v[126:127], v[120:121], v[122:123]
	s_waitcnt lgkmcnt(0)
	v_pk_mul_f32 v[124:125], v[128:129], v[124:125]
	v_mul_f32_e32 v127, 0x3c23d70b, v130
	v_mul_f32_e32 v129, 0x3b4f3e39, v130
	v_cos_f32_e32 v122, v131
	v_cos_f32_e32 v123, v132
	ds_bpermute_b32 v126, v146, v116
	v_mul_f32_e32 v131, 0.15915494, v127
	ds_bpermute_b32 v127, v146, v117
	v_mul_f32_e32 v132, 0.15915494, v129
	v_sin_f32_e32 v128, v131
	v_sin_f32_e32 v129, v132
	v_cndmask_b32_e64 v125, v125, -v125, s[2:3]
	v_cndmask_b32_e64 v124, v124, -v124, s[2:3]
	v_pk_fma_f32 v[118:119], v[122:123], v[118:119], v[124:125]
	v_cos_f32_e32 v122, v131
	v_cos_f32_e32 v123, v132
	s_waitcnt lgkmcnt(0)
	v_pk_mul_f32 v[124:125], v[128:129], v[126:127]
	v_mul_f32_e32 v127, 0x3a831270, v130
	v_mul_f32_e32 v129, 0x39a5cb61, v130
	ds_bpermute_b32 v126, v146, v114
	v_mul_f32_e32 v131, 0.15915494, v127
	ds_bpermute_b32 v127, v146, v115
	v_mul_f32_e32 v130, 0.15915494, v129
	v_sin_f32_e32 v128, v131
	v_sin_f32_e32 v129, v130
	v_cndmask_b32_e64 v125, v125, -v125, s[2:3]
	v_cndmask_b32_e64 v124, v124, -v124, s[2:3]
	v_pk_fma_f32 v[116:117], v[122:123], v[116:117], v[124:125]
	v_cos_f32_e32 v122, v131
	v_cos_f32_e32 v123, v130
	s_waitcnt lgkmcnt(0)
	v_pk_mul_f32 v[124:125], v[128:129], v[126:127]
	s_nop 0
	v_cndmask_b32_e64 v125, v125, -v125, s[2:3]
	v_cndmask_b32_e64 v124, v124, -v124, s[2:3]
	v_pk_fma_f32 v[114:115], v[122:123], v[114:115], v[124:125]

.LBB0_632:
	v_mul_f32_e32 v127, v111, v111
	v_fmac_f32_e32 v127, v110, v110
	v_fmac_f32_e32 v127, v112, v112
	v_fmac_f32_e32 v127, v113, v113
	v_fmac_f32_e32 v127, v106, v106
	v_fmac_f32_e32 v127, v107, v107
	v_fmac_f32_e32 v127, v108, v108
	v_fmac_f32_e32 v127, v109, v109
	v_fmac_f32_e32 v127, v102, v102
	v_fmac_f32_e32 v127, v103, v103
	v_fmac_f32_e32 v127, v104, v104
	v_fmac_f32_e32 v127, v105, v105
	v_fmac_f32_e32 v127, v98, v98
	v_fmac_f32_e32 v127, v99, v99
	v_fmac_f32_e32 v127, v100, v100
	v_pk_mul_f32 v[136:137], v[114:115], v[114:115]
	v_fmac_f32_e32 v127, v101, v101
	v_add_f32_e32 v127, v127, v136
	v_pk_mul_f32 v[142:143], v[116:117], v[116:117]
	v_add_f32_e32 v127, v137, v127
	v_add_f32_e32 v127, v142, v127
	v_pk_mul_f32 v[144:145], v[118:119], v[118:119]
	v_add_f32_e32 v127, v143, v127
	v_add_f32_e32 v127, v144, v127
	v_pk_mul_f32 v[150:151], v[120:121], v[120:121]
	v_add_f32_e32 v127, v145, v127
	v_add_f32_e32 v127, v150, v127
	v_add_f32_e32 v127, v151, v127
	v_mov_b32_e32 v129, v127
	s_nop 1
	v_permlane16_swap_b32_e32 v129, v127
	v_mov_b64_e32 v[136:137], s[24:25]
	v_lshlrev_b32_e32 v126, 1, v126
	s_waitcnt lgkmcnt(0)
	v_add_f32_e32 v129, v127, v129
	v_mov_b32_e32 v131, v129
	s_nop 1
	v_permlane32_swap_b32_e32 v131, v129
	v_mov_b32_e32 v127, v163
	s_waitcnt lgkmcnt(0)
	v_add_f32_e32 v129, v129, v131
	v_fmamk_f32 v129, v129, 0x3c2aaaab, v1
	v_mul_f32_e32 v131, 0x4b800000, v129
	v_cmp_gt_f32_e32 vcc, s56, v129
	s_nop 1
	v_cndmask_b32_e32 v129, v129, v131, vcc
	v_rsq_f32_e32 v131, v129
	v_mad_i64_i32 v[128:129], s[6:7], v128, s57, v[136:137]
	v_lshl_add_u64 v[128:129], v[140:141], 1, v[128:129]
	v_lshl_add_u64 v[136:137], v[128:129], 0, v[126:127]
	v_mul_f32_e32 v127, 0x45800000, v131
	v_cndmask_b32_e32 v142, v131, v127, vcc
	v_mul_f32_e32 v110, v110, v142
	v_mul_f32_e32 v111, v111, v142
	v_mul_f32_e32 v112, v112, v142
	v_mul_f32_e32 v113, v113, v142
	v_mul_f32_e32 v106, v106, v142
	v_mul_f32_e32 v107, v107, v142
	v_mul_f32_e32 v108, v108, v142
	v_mul_f32_e32 v109, v109, v142
	v_mul_f32_e32 v102, v102, v142
	v_mul_f32_e32 v103, v103, v142
	v_mul_f32_e32 v104, v104, v142
	v_mul_f32_e32 v105, v105, v142
	v_mul_f32_e32 v98, v98, v142
	v_mul_f32_e32 v99, v99, v142
	v_mul_f32_e32 v100, v100, v142
	v_mul_f32_e32 v101, v101, v142
	s_andn2_b64 vcc, exec, s[30:31]
	v_mul_f32_e32 v110, v170, v110
	v_mul_f32_e32 v111, v171, v111
	v_mul_f32_e32 v112, v172, v112
	v_mul_f32_e32 v113, v173, v113
	v_cvt_pk_bf16_f32 v110, v110, v111
	v_cvt_pk_bf16_f32 v111, v112, v113
	global_store_dwordx2 v[136:137], v[110:111], off
	v_mul_f32_e32 v106, v174, v106
	v_mul_f32_e32 v107, v175, v107
	v_mul_f32_e32 v108, v176, v108
	v_mul_f32_e32 v109, v177, v109
	v_cvt_pk_bf16_f32 v106, v106, v107
	v_cvt_pk_bf16_f32 v107, v108, v109
	global_store_dwordx2 v[136:137], v[106:107], off offset:32
	v_mul_f32_e32 v102, v178, v102
	v_mul_f32_e32 v103, v179, v103
	v_mul_f32_e32 v104, v180, v104
	v_mul_f32_e32 v105, v105, v181
	v_cvt_pk_bf16_f32 v102, v102, v103
	v_cvt_pk_bf16_f32 v103, v104, v105
	global_store_dwordx2 v[136:137], v[102:103], off offset:64
	v_cndmask_b32_e64 v106, 0, 1, s[30:31]
	v_cmp_ne_u32_e64 s[6:7], 1, v106
	v_mul_f32_e32 v98, v98, v182
	v_mul_f32_e32 v99, v99, v183
	v_mul_f32_e32 v100, v100, v184
	v_mul_f32_e32 v101, v101, v185
	v_cvt_pk_bf16_f32 v98, v98, v99
	v_cvt_pk_bf16_f32 v99, v100, v101
	global_store_dwordx2 v[136:137], v[98:99], off offset:96
	s_nop 0
	v_mov_b32_e32 v98, v186
	v_mov_b32_e32 v99, v187
	v_mov_b32_e32 v100, v188
	v_mov_b32_e32 v101, v189
	v_pk_mul_f32 v[98:99], v[142:143], v[98:99] op_sel_hi:[0,1]
	v_pk_mul_f32 v[100:101], v[142:143], v[100:101] op_sel_hi:[0,1]
	v_pk_mul_f32 v[106:107], v[142:143], v[190:191] op_sel_hi:[0,1]
	v_pk_mul_f32 v[108:109], v[142:143], v[192:193] op_sel_hi:[0,1]
	v_pk_mul_f32 v[104:105], v[114:115], v[98:99]
	v_pk_mul_f32 v[102:103], v[116:117], v[100:101]
	v_pk_mul_f32 v[100:101], v[118:119], v[106:107]
	v_pk_mul_f32 v[98:99], v[120:121], v[108:109]
	s_cbranch_vccnz .LBB0_634
	v_add_u32_e32 v106, s60, v130
	v_ashrrev_i32_e32 v107, 6, v106
	v_and_b32_e32 v106, 63, v106
	v_cndmask_b32_e64 v106, v106, v107, s[4:5]
	v_cvt_f32_i32_e32 v114, v106
	ds_bpermute_b32 v106, v146, v104
	ds_bpermute_b32 v107, v146, v105
	v_mul_f32_e32 v109, 0x3ea1e89b, v114
	v_mul_f32_e32 v110, 0.15915494, v114
	v_mul_f32_e32 v111, 0.15915494, v109
	v_sin_f32_e32 v108, v110
	v_sin_f32_e32 v109, v111
	v_mul_f32_e32 v113, 0x3d0186e3, v114
	v_mul_f32_e32 v116, 0.15915494, v113
	v_cos_f32_e32 v110, v110
	s_waitcnt lgkmcnt(0)
	v_pk_mul_f32 v[106:107], v[108:109], v[106:107]
	v_mul_f32_e32 v109, 0x3dcccccd, v114
	ds_bpermute_b32 v108, v146, v102
	v_mul_f32_e32 v115, 0.15915494, v109
	ds_bpermute_b32 v109, v146, v103
	v_cos_f32_e32 v111, v111
	v_sin_f32_e32 v112, v115
	v_sin_f32_e32 v113, v116
	v_cndmask_b32_e64 v107, v107, -v107, s[2:3]
	v_cndmask_b32_e64 v106, v106, -v106, s[2:3]
	v_pk_fma_f32 v[104:105], v[110:111], v[104:105], v[106:107]
	s_waitcnt lgkmcnt(0)
	v_pk_mul_f32 v[108:109], v[112:113], v[108:109]
	v_mul_f32_e32 v111, 0x3c23d70b, v114
	v_mul_f32_e32 v113, 0x3b4f3e39, v114
	v_cos_f32_e32 v106, v115
	v_cos_f32_e32 v107, v116
	ds_bpermute_b32 v110, v146, v100
	v_mul_f32_e32 v115, 0.15915494, v111
	ds_bpermute_b32 v111, v146, v101
	v_mul_f32_e32 v116, 0.15915494, v113
	v_sin_f32_e32 v112, v115
	v_sin_f32_e32 v113, v116
	v_cndmask_b32_e64 v109, v109, -v109, s[2:3]
	v_cndmask_b32_e64 v108, v108, -v108, s[2:3]
	v_pk_fma_f32 v[102:103], v[106:107], v[102:103], v[108:109]
	v_cos_f32_e32 v106, v115
	v_cos_f32_e32 v107, v116
	s_waitcnt lgkmcnt(0)
	v_pk_mul_f32 v[108:109], v[112:113], v[110:111]
	v_mul_f32_e32 v111, 0x3a831270, v114
	v_mul_f32_e32 v113, 0x39a5cb61, v114
	ds_bpermute_b32 v110, v146, v98
	v_mul_f32_e32 v115, 0.15915494, v111
	ds_bpermute_b32 v111, v146, v99
	v_mul_f32_e32 v114, 0.15915494, v113
	v_sin_f32_e32 v112, v115
	v_sin_f32_e32 v113, v114
	v_cndmask_b32_e64 v109, v109, -v109, s[2:3]
	v_cndmask_b32_e64 v108, v108, -v108, s[2:3]
	v_pk_fma_f32 v[100:101], v[106:107], v[100:101], v[108:109]
	v_cos_f32_e32 v106, v115
	v_cos_f32_e32 v107, v114
	s_waitcnt lgkmcnt(0)
	v_pk_mul_f32 v[108:109], v[112:113], v[110:111]
	s_nop 0
	v_cndmask_b32_e64 v109, v109, -v109, s[2:3]
	v_cndmask_b32_e64 v108, v108, -v108, s[2:3]
	v_pk_fma_f32 v[98:99], v[106:107], v[98:99], v[108:109]

.LBB0_640:
	v_mul_f32_e32 v107, v95, v95
	v_fmac_f32_e32 v107, v94, v94
	v_fmac_f32_e32 v107, v96, v96
	v_fmac_f32_e32 v107, v97, v97
	v_fmac_f32_e32 v107, v90, v90
	v_fmac_f32_e32 v107, v91, v91
	v_fmac_f32_e32 v107, v92, v92
	v_fmac_f32_e32 v107, v93, v93
	v_fmac_f32_e32 v107, v86, v86
	v_fmac_f32_e32 v107, v87, v87
	v_fmac_f32_e32 v107, v88, v88
	v_fmac_f32_e32 v107, v89, v89
	v_fmac_f32_e32 v107, v82, v82
	v_fmac_f32_e32 v107, v83, v83
	v_fmac_f32_e32 v107, v84, v84
	v_pk_mul_f32 v[114:115], v[98:99], v[98:99]
	v_fmac_f32_e32 v107, v85, v85
	v_add_f32_e32 v107, v107, v114
	v_pk_mul_f32 v[116:117], v[100:101], v[100:101]
	v_add_f32_e32 v107, v115, v107
	v_add_f32_e32 v107, v116, v107
	v_pk_mul_f32 v[118:119], v[102:103], v[102:103]
	v_add_f32_e32 v107, v117, v107
	v_add_f32_e32 v107, v118, v107
	v_pk_mul_f32 v[120:121], v[104:105], v[104:105]
	v_add_f32_e32 v107, v119, v107
	v_add_f32_e32 v107, v120, v107
	v_add_f32_e32 v107, v121, v107
	v_mov_b32_e32 v109, v107
	s_nop 1
	v_permlane16_swap_b32_e32 v109, v107
	v_mov_b64_e32 v[114:115], s[24:25]
	v_mov_b32_e32 v127, v163
	s_waitcnt lgkmcnt(0)
	v_add_f32_e32 v107, v107, v109
	v_mov_b32_e32 v109, v107
	s_nop 1
	v_permlane32_swap_b32_e32 v109, v107
	s_waitcnt lgkmcnt(0)
	v_add_f32_e32 v107, v107, v109
	v_fmamk_f32 v107, v107, 0x3c2aaaab, v1
	v_mul_f32_e32 v109, 0x4b800000, v107
	v_cmp_gt_f32_e32 vcc, s56, v107
	s_nop 1
	v_cndmask_b32_e32 v107, v107, v109, vcc
	v_rsq_f32_e32 v109, v107
	v_mad_i64_i32 v[106:107], s[30:31], v106, s57, v[114:115]
	v_lshl_add_u64 v[106:107], v[140:141], 1, v[106:107]
	v_mul_f32_e32 v116, 0x45800000, v109
	v_cndmask_b32_e32 v116, v109, v116, vcc
	v_mul_f32_e32 v94, v94, v116
	v_mul_f32_e32 v95, v95, v116
	v_lshl_add_u64 v[114:115], v[106:107], 0, v[126:127]
	v_mul_f32_e32 v96, v96, v116
	v_mul_f32_e32 v97, v97, v116
	v_mul_f32_e32 v90, v90, v116
	v_mul_f32_e32 v91, v91, v116
	v_mul_f32_e32 v92, v92, v116
	v_mul_f32_e32 v93, v93, v116
	v_mul_f32_e32 v86, v86, v116
	v_mul_f32_e32 v87, v87, v116
	v_mul_f32_e32 v88, v88, v116
	v_mul_f32_e32 v89, v89, v116
	v_mul_f32_e32 v82, v82, v116
	v_mul_f32_e32 v83, v83, v116
	v_mul_f32_e32 v84, v84, v116
	v_mul_f32_e32 v85, v85, v116
	s_and_b64 vcc, exec, s[6:7]
	v_mul_f32_e32 v94, v170, v94
	v_mul_f32_e32 v95, v171, v95
	v_mul_f32_e32 v96, v172, v96
	v_mul_f32_e32 v97, v173, v97
	v_cvt_pk_bf16_f32 v94, v94, v95
	v_cvt_pk_bf16_f32 v95, v96, v97
	global_store_dwordx2 v[114:115], v[94:95], off
	v_mul_f32_e32 v90, v174, v90
	v_mul_f32_e32 v91, v175, v91
	v_mul_f32_e32 v92, v176, v92
	v_mul_f32_e32 v93, v177, v93
	v_cvt_pk_bf16_f32 v90, v90, v91
	v_cvt_pk_bf16_f32 v91, v92, v93
	global_store_dwordx2 v[114:115], v[90:91], off offset:32
	v_mul_f32_e32 v86, v178, v86
	v_mul_f32_e32 v87, v179, v87
	v_mul_f32_e32 v88, v180, v88
	v_mul_f32_e32 v89, v89, v181
	v_cvt_pk_bf16_f32 v86, v86, v87
	v_cvt_pk_bf16_f32 v87, v88, v89
	global_store_dwordx2 v[114:115], v[86:87], off offset:64
	v_mul_f32_e32 v82, v82, v182
	v_mul_f32_e32 v83, v83, v183
	v_mul_f32_e32 v84, v84, v184
	v_mul_f32_e32 v85, v85, v185
	v_cvt_pk_bf16_f32 v82, v82, v83
	v_cvt_pk_bf16_f32 v83, v84, v85
	global_store_dwordx2 v[114:115], v[82:83], off offset:96
	s_nop 0
	v_mov_b32_e32 v82, v186
	v_mov_b32_e32 v83, v187
	v_mov_b32_e32 v84, v188
	v_mov_b32_e32 v85, v189
	v_pk_mul_f32 v[82:83], v[116:117], v[82:83] op_sel_hi:[0,1]
	v_pk_mul_f32 v[84:85], v[116:117], v[84:85] op_sel_hi:[0,1]
	v_pk_mul_f32 v[90:91], v[116:117], v[190:191] op_sel_hi:[0,1]
	v_pk_mul_f32 v[92:93], v[116:117], v[192:193] op_sel_hi:[0,1]
	v_pk_mul_f32 v[88:89], v[98:99], v[82:83]
	v_pk_mul_f32 v[86:87], v[100:101], v[84:85]
	v_pk_mul_f32 v[84:85], v[102:103], v[90:91]
	v_pk_mul_f32 v[82:83], v[104:105], v[92:93]
	s_cbranch_vccnz .LBB0_642
	v_add_u32_e32 v90, s60, v108
	v_ashrrev_i32_e32 v91, 6, v90
	v_and_b32_e32 v90, 63, v90
	v_cndmask_b32_e64 v90, v90, v91, s[4:5]
	v_cvt_f32_i32_e32 v98, v90
	ds_bpermute_b32 v90, v146, v88
	ds_bpermute_b32 v91, v146, v89
	v_mul_f32_e32 v93, 0x3ea1e89b, v98
	v_mul_f32_e32 v94, 0.15915494, v98
	v_mul_f32_e32 v95, 0.15915494, v93
	v_sin_f32_e32 v92, v94
	v_sin_f32_e32 v93, v95
	v_mul_f32_e32 v97, 0x3d0186e3, v98
	v_mul_f32_e32 v100, 0.15915494, v97
	v_cos_f32_e32 v94, v94
	s_waitcnt lgkmcnt(0)
	v_pk_mul_f32 v[90:91], v[92:93], v[90:91]
	v_mul_f32_e32 v93, 0x3dcccccd, v98
	ds_bpermute_b32 v92, v146, v86
	v_mul_f32_e32 v99, 0.15915494, v93
	ds_bpermute_b32 v93, v146, v87
	v_cos_f32_e32 v95, v95
	v_sin_f32_e32 v96, v99
	v_sin_f32_e32 v97, v100
	v_cndmask_b32_e64 v91, v91, -v91, s[2:3]
	v_cndmask_b32_e64 v90, v90, -v90, s[2:3]
	v_pk_fma_f32 v[88:89], v[94:95], v[88:89], v[90:91]
	s_waitcnt lgkmcnt(0)
	v_pk_mul_f32 v[92:93], v[96:97], v[92:93]
	v_mul_f32_e32 v95, 0x3c23d70b, v98
	v_mul_f32_e32 v97, 0x3b4f3e39, v98
	v_cos_f32_e32 v90, v99
	v_cos_f32_e32 v91, v100
	ds_bpermute_b32 v94, v146, v84
	v_mul_f32_e32 v99, 0.15915494, v95
	ds_bpermute_b32 v95, v146, v85
	v_mul_f32_e32 v100, 0.15915494, v97
	v_sin_f32_e32 v96, v99
	v_sin_f32_e32 v97, v100
	v_cndmask_b32_e64 v93, v93, -v93, s[2:3]
	v_cndmask_b32_e64 v92, v92, -v92, s[2:3]
	v_pk_fma_f32 v[86:87], v[90:91], v[86:87], v[92:93]
	v_cos_f32_e32 v90, v99
	v_cos_f32_e32 v91, v100
	s_waitcnt lgkmcnt(0)
	v_pk_mul_f32 v[92:93], v[96:97], v[94:95]
	v_mul_f32_e32 v95, 0x3a831270, v98
	v_mul_f32_e32 v97, 0x39a5cb61, v98
	ds_bpermute_b32 v94, v146, v82
	v_mul_f32_e32 v99, 0.15915494, v95
	ds_bpermute_b32 v95, v146, v83
	v_mul_f32_e32 v98, 0.15915494, v97
	v_sin_f32_e32 v96, v99
	v_sin_f32_e32 v97, v98
	v_cndmask_b32_e64 v93, v93, -v93, s[2:3]
	v_cndmask_b32_e64 v92, v92, -v92, s[2:3]
	v_pk_fma_f32 v[84:85], v[90:91], v[84:85], v[92:93]
	v_cos_f32_e32 v90, v99
	v_cos_f32_e32 v91, v98
	s_waitcnt lgkmcnt(0)
	v_pk_mul_f32 v[92:93], v[96:97], v[94:95]
	s_nop 0
	v_cndmask_b32_e64 v93, v93, -v93, s[2:3]
	v_cndmask_b32_e64 v92, v92, -v92, s[2:3]
	v_pk_fma_f32 v[82:83], v[90:91], v[82:83], v[92:93]

.LBB0_648:
	v_mul_f32_e32 v91, v79, v79
	v_fmac_f32_e32 v91, v78, v78
	v_fmac_f32_e32 v91, v80, v80
	v_fmac_f32_e32 v91, v81, v81
	v_fmac_f32_e32 v91, v74, v74
	v_fmac_f32_e32 v91, v75, v75
	v_fmac_f32_e32 v91, v76, v76
	v_fmac_f32_e32 v91, v77, v77
	v_fmac_f32_e32 v91, v70, v70
	v_fmac_f32_e32 v91, v71, v71
	v_fmac_f32_e32 v91, v72, v72
	v_fmac_f32_e32 v91, v73, v73
	v_fmac_f32_e32 v91, v66, v66
	v_fmac_f32_e32 v91, v67, v67
	v_fmac_f32_e32 v91, v68, v68
	v_pk_mul_f32 v[98:99], v[82:83], v[82:83]
	v_fmac_f32_e32 v91, v69, v69
	v_add_f32_e32 v91, v91, v98
	v_pk_mul_f32 v[100:101], v[84:85], v[84:85]
	v_add_f32_e32 v91, v99, v91
	v_add_f32_e32 v91, v100, v91
	v_pk_mul_f32 v[102:103], v[86:87], v[86:87]
	v_add_f32_e32 v91, v101, v91
	v_add_f32_e32 v91, v102, v91
	v_pk_mul_f32 v[104:105], v[88:89], v[88:89]
	v_add_f32_e32 v91, v103, v91
	v_add_f32_e32 v91, v104, v91
	v_add_f32_e32 v91, v105, v91
	v_mov_b32_e32 v93, v91
	s_nop 1
	v_permlane16_swap_b32_e32 v93, v91
	v_mov_b64_e32 v[98:99], s[24:25]
	v_mov_b32_e32 v127, v163
	s_waitcnt lgkmcnt(0)
	v_add_f32_e32 v91, v91, v93
	v_mov_b32_e32 v93, v91
	s_nop 1
	v_permlane32_swap_b32_e32 v93, v91
	s_waitcnt lgkmcnt(0)
	v_add_f32_e32 v91, v91, v93
	v_fmamk_f32 v91, v91, 0x3c2aaaab, v1
	v_mul_f32_e32 v93, 0x4b800000, v91
	v_cmp_gt_f32_e32 vcc, s56, v91
	s_nop 1
	v_cndmask_b32_e32 v91, v91, v93, vcc
	v_rsq_f32_e32 v93, v91
	v_mad_i64_i32 v[90:91], s[30:31], v90, s57, v[98:99]
	v_lshl_add_u64 v[90:91], v[140:141], 1, v[90:91]
	v_mul_f32_e32 v100, 0x45800000, v93
	v_cndmask_b32_e32 v100, v93, v100, vcc
	v_mul_f32_e32 v78, v78, v100
	v_mul_f32_e32 v79, v79, v100
	v_lshl_add_u64 v[98:99], v[90:91], 0, v[126:127]
	v_mul_f32_e32 v80, v80, v100
	v_mul_f32_e32 v81, v81, v100
	v_mul_f32_e32 v74, v74, v100
	v_mul_f32_e32 v75, v75, v100
	v_mul_f32_e32 v76, v76, v100
	v_mul_f32_e32 v77, v77, v100
	v_mul_f32_e32 v70, v70, v100
	v_mul_f32_e32 v71, v71, v100
	v_mul_f32_e32 v72, v72, v100
	v_mul_f32_e32 v73, v73, v100
	v_mul_f32_e32 v66, v66, v100
	v_mul_f32_e32 v67, v67, v100
	v_mul_f32_e32 v68, v68, v100
	v_mul_f32_e32 v69, v69, v100
	s_and_b64 vcc, exec, s[6:7]
	v_mul_f32_e32 v78, v170, v78
	v_mul_f32_e32 v79, v171, v79
	v_mul_f32_e32 v80, v172, v80
	v_mul_f32_e32 v81, v173, v81
	v_cvt_pk_bf16_f32 v78, v78, v79
	v_cvt_pk_bf16_f32 v79, v80, v81
	global_store_dwordx2 v[98:99], v[78:79], off
	v_mul_f32_e32 v74, v174, v74
	v_mul_f32_e32 v75, v175, v75
	v_mul_f32_e32 v76, v176, v76
	v_mul_f32_e32 v77, v177, v77
	v_cvt_pk_bf16_f32 v74, v74, v75
	v_cvt_pk_bf16_f32 v75, v76, v77
	global_store_dwordx2 v[98:99], v[74:75], off offset:32
	v_mul_f32_e32 v70, v178, v70
	v_mul_f32_e32 v71, v179, v71
	v_mul_f32_e32 v72, v180, v72
	v_mul_f32_e32 v73, v73, v181
	v_cvt_pk_bf16_f32 v70, v70, v71
	v_cvt_pk_bf16_f32 v71, v72, v73
	global_store_dwordx2 v[98:99], v[70:71], off offset:64
	v_mul_f32_e32 v66, v66, v182
	v_mul_f32_e32 v67, v67, v183
	v_mul_f32_e32 v68, v68, v184
	v_mul_f32_e32 v69, v69, v185
	v_cvt_pk_bf16_f32 v66, v66, v67
	v_cvt_pk_bf16_f32 v67, v68, v69
	global_store_dwordx2 v[98:99], v[66:67], off offset:96
	s_nop 0
	v_mov_b32_e32 v66, v186
	v_mov_b32_e32 v67, v187
	v_mov_b32_e32 v68, v188
	v_mov_b32_e32 v69, v189
	v_pk_mul_f32 v[66:67], v[100:101], v[66:67] op_sel_hi:[0,1]
	v_pk_mul_f32 v[68:69], v[100:101], v[68:69] op_sel_hi:[0,1]
	v_pk_mul_f32 v[74:75], v[100:101], v[190:191] op_sel_hi:[0,1]
	v_pk_mul_f32 v[76:77], v[100:101], v[192:193] op_sel_hi:[0,1]
	v_pk_mul_f32 v[72:73], v[82:83], v[66:67]
	v_pk_mul_f32 v[70:71], v[84:85], v[68:69]
	v_pk_mul_f32 v[68:69], v[86:87], v[74:75]
	v_pk_mul_f32 v[66:67], v[88:89], v[76:77]
	s_cbranch_vccnz .LBB0_650
	v_add_u32_e32 v74, s60, v92
	v_ashrrev_i32_e32 v75, 6, v74
	v_and_b32_e32 v74, 63, v74
	v_cndmask_b32_e64 v74, v74, v75, s[4:5]
	v_cvt_f32_i32_e32 v82, v74
	ds_bpermute_b32 v74, v146, v72
	ds_bpermute_b32 v75, v146, v73
	v_mul_f32_e32 v77, 0x3ea1e89b, v82
	v_mul_f32_e32 v78, 0.15915494, v82
	v_mul_f32_e32 v79, 0.15915494, v77
	v_sin_f32_e32 v76, v78
	v_sin_f32_e32 v77, v79
	v_mul_f32_e32 v81, 0x3d0186e3, v82
	v_mul_f32_e32 v84, 0.15915494, v81
	v_cos_f32_e32 v78, v78
	s_waitcnt lgkmcnt(0)
	v_pk_mul_f32 v[74:75], v[76:77], v[74:75]
	v_mul_f32_e32 v77, 0x3dcccccd, v82
	ds_bpermute_b32 v76, v146, v70
	v_mul_f32_e32 v83, 0.15915494, v77
	ds_bpermute_b32 v77, v146, v71
	v_cos_f32_e32 v79, v79
	v_sin_f32_e32 v80, v83
	v_sin_f32_e32 v81, v84
	v_cndmask_b32_e64 v75, v75, -v75, s[2:3]
	v_cndmask_b32_e64 v74, v74, -v74, s[2:3]
	v_pk_fma_f32 v[72:73], v[78:79], v[72:73], v[74:75]
	s_waitcnt lgkmcnt(0)
	v_pk_mul_f32 v[76:77], v[80:81], v[76:77]
	v_mul_f32_e32 v79, 0x3c23d70b, v82
	v_mul_f32_e32 v81, 0x3b4f3e39, v82
	v_cos_f32_e32 v74, v83
	v_cos_f32_e32 v75, v84
	ds_bpermute_b32 v78, v146, v68
	v_mul_f32_e32 v83, 0.15915494, v79
	ds_bpermute_b32 v79, v146, v69
	v_mul_f32_e32 v84, 0.15915494, v81
	v_sin_f32_e32 v80, v83
	v_sin_f32_e32 v81, v84
	v_cndmask_b32_e64 v77, v77, -v77, s[2:3]
	v_cndmask_b32_e64 v76, v76, -v76, s[2:3]
	v_pk_fma_f32 v[70:71], v[74:75], v[70:71], v[76:77]
	v_cos_f32_e32 v74, v83
	v_cos_f32_e32 v75, v84
	s_waitcnt lgkmcnt(0)
	v_pk_mul_f32 v[76:77], v[80:81], v[78:79]
	v_mul_f32_e32 v79, 0x3a831270, v82
	v_mul_f32_e32 v81, 0x39a5cb61, v82
	ds_bpermute_b32 v78, v146, v66
	v_mul_f32_e32 v83, 0.15915494, v79
	ds_bpermute_b32 v79, v146, v67
	v_mul_f32_e32 v82, 0.15915494, v81
	v_sin_f32_e32 v80, v83
	v_sin_f32_e32 v81, v82
	v_cndmask_b32_e64 v77, v77, -v77, s[2:3]
	v_cndmask_b32_e64 v76, v76, -v76, s[2:3]
	v_pk_fma_f32 v[68:69], v[74:75], v[68:69], v[76:77]
	v_cos_f32_e32 v74, v83
	v_cos_f32_e32 v75, v82
	s_waitcnt lgkmcnt(0)
	v_pk_mul_f32 v[76:77], v[80:81], v[78:79]
	s_nop 0
	v_cndmask_b32_e64 v77, v77, -v77, s[2:3]
	v_cndmask_b32_e64 v76, v76, -v76, s[2:3]
	v_pk_fma_f32 v[66:67], v[74:75], v[66:67], v[76:77]

.LBB0_656:
	v_mul_f32_e32 v75, v63, v63
	v_fmac_f32_e32 v75, v62, v62
	v_fmac_f32_e32 v75, v64, v64
	v_fmac_f32_e32 v75, v65, v65
	v_fmac_f32_e32 v75, v58, v58
	v_fmac_f32_e32 v75, v59, v59
	v_fmac_f32_e32 v75, v60, v60
	v_fmac_f32_e32 v75, v61, v61
	v_fmac_f32_e32 v75, v54, v54
	v_fmac_f32_e32 v75, v55, v55
	v_fmac_f32_e32 v75, v56, v56
	v_fmac_f32_e32 v75, v57, v57
	v_fmac_f32_e32 v75, v50, v50
	v_fmac_f32_e32 v75, v51, v51
	v_fmac_f32_e32 v75, v52, v52
	v_pk_mul_f32 v[82:83], v[66:67], v[66:67]
	v_fmac_f32_e32 v75, v53, v53
	v_add_f32_e32 v75, v75, v82
	v_pk_mul_f32 v[84:85], v[68:69], v[68:69]
	v_add_f32_e32 v75, v83, v75
	v_add_f32_e32 v75, v84, v75
	v_pk_mul_f32 v[86:87], v[70:71], v[70:71]
	v_add_f32_e32 v75, v85, v75
	v_add_f32_e32 v75, v86, v75
	v_pk_mul_f32 v[88:89], v[72:73], v[72:73]
	v_add_f32_e32 v75, v87, v75
	v_add_f32_e32 v75, v88, v75
	v_add_f32_e32 v75, v89, v75
	v_mov_b32_e32 v77, v75
	s_nop 1
	v_permlane16_swap_b32_e32 v77, v75
	v_mov_b64_e32 v[82:83], s[24:25]
	v_mov_b32_e32 v127, v163
	s_waitcnt lgkmcnt(0)
	v_add_f32_e32 v75, v75, v77
	v_mov_b32_e32 v77, v75
	s_nop 1
	v_permlane32_swap_b32_e32 v77, v75
	s_waitcnt lgkmcnt(0)
	v_add_f32_e32 v75, v75, v77
	v_fmamk_f32 v75, v75, 0x3c2aaaab, v1
	v_mul_f32_e32 v77, 0x4b800000, v75
	v_cmp_gt_f32_e32 vcc, s56, v75
	s_nop 1
	v_cndmask_b32_e32 v75, v75, v77, vcc
	v_rsq_f32_e32 v77, v75
	v_mad_i64_i32 v[74:75], s[30:31], v74, s57, v[82:83]
	v_lshl_add_u64 v[74:75], v[140:141], 1, v[74:75]
	v_mul_f32_e32 v84, 0x45800000, v77
	v_cndmask_b32_e32 v84, v77, v84, vcc
	v_mul_f32_e32 v62, v62, v84
	v_mul_f32_e32 v63, v63, v84
	v_lshl_add_u64 v[82:83], v[74:75], 0, v[126:127]
	v_mul_f32_e32 v64, v64, v84
	v_mul_f32_e32 v65, v65, v84
	v_mul_f32_e32 v58, v58, v84
	v_mul_f32_e32 v59, v59, v84
	v_mul_f32_e32 v60, v60, v84
	v_mul_f32_e32 v61, v61, v84
	v_mul_f32_e32 v54, v54, v84
	v_mul_f32_e32 v55, v55, v84
	v_mul_f32_e32 v56, v56, v84
	v_mul_f32_e32 v57, v57, v84
	v_mul_f32_e32 v50, v50, v84
	v_mul_f32_e32 v51, v51, v84
	v_mul_f32_e32 v52, v52, v84
	v_mul_f32_e32 v53, v53, v84
	s_and_b64 vcc, exec, s[6:7]
	v_mul_f32_e32 v62, v170, v62
	v_mul_f32_e32 v63, v171, v63
	v_mul_f32_e32 v64, v172, v64
	v_mul_f32_e32 v65, v173, v65
	v_cvt_pk_bf16_f32 v62, v62, v63
	v_cvt_pk_bf16_f32 v63, v64, v65
	global_store_dwordx2 v[82:83], v[62:63], off
	v_mul_f32_e32 v58, v174, v58
	v_mul_f32_e32 v59, v175, v59
	v_mul_f32_e32 v60, v176, v60
	v_mul_f32_e32 v61, v177, v61
	v_cvt_pk_bf16_f32 v58, v58, v59
	v_cvt_pk_bf16_f32 v59, v60, v61
	global_store_dwordx2 v[82:83], v[58:59], off offset:32
	v_mul_f32_e32 v54, v178, v54
	v_mul_f32_e32 v55, v179, v55
	v_mul_f32_e32 v56, v180, v56
	v_mul_f32_e32 v57, v57, v181
	v_cvt_pk_bf16_f32 v54, v54, v55
	v_cvt_pk_bf16_f32 v55, v56, v57
	global_store_dwordx2 v[82:83], v[54:55], off offset:64
	v_mul_f32_e32 v50, v50, v182
	v_mul_f32_e32 v51, v51, v183
	v_mul_f32_e32 v52, v52, v184
	v_mul_f32_e32 v53, v53, v185
	v_cvt_pk_bf16_f32 v50, v50, v51
	v_cvt_pk_bf16_f32 v51, v52, v53
	global_store_dwordx2 v[82:83], v[50:51], off offset:96
	s_nop 0
	v_mov_b32_e32 v50, v186
	v_mov_b32_e32 v51, v187
	v_mov_b32_e32 v52, v188
	v_mov_b32_e32 v53, v189
	v_pk_mul_f32 v[50:51], v[84:85], v[50:51] op_sel_hi:[0,1]
	v_pk_mul_f32 v[52:53], v[84:85], v[52:53] op_sel_hi:[0,1]
	v_pk_mul_f32 v[58:59], v[84:85], v[190:191] op_sel_hi:[0,1]
	v_pk_mul_f32 v[60:61], v[84:85], v[192:193] op_sel_hi:[0,1]
	v_pk_mul_f32 v[56:57], v[66:67], v[50:51]
	v_pk_mul_f32 v[54:55], v[68:69], v[52:53]
	v_pk_mul_f32 v[52:53], v[70:71], v[58:59]
	v_pk_mul_f32 v[50:51], v[72:73], v[60:61]
	s_cbranch_vccnz .LBB0_658
	v_add_u32_e32 v58, s60, v76
	v_ashrrev_i32_e32 v59, 6, v58
	v_and_b32_e32 v58, 63, v58
	v_cndmask_b32_e64 v58, v58, v59, s[4:5]
	v_cvt_f32_i32_e32 v66, v58
	ds_bpermute_b32 v58, v146, v56
	ds_bpermute_b32 v59, v146, v57
	v_mul_f32_e32 v61, 0x3ea1e89b, v66
	v_mul_f32_e32 v62, 0.15915494, v66
	v_mul_f32_e32 v63, 0.15915494, v61
	v_sin_f32_e32 v60, v62
	v_sin_f32_e32 v61, v63
	v_mul_f32_e32 v65, 0x3d0186e3, v66
	v_mul_f32_e32 v68, 0.15915494, v65
	v_cos_f32_e32 v62, v62
	s_waitcnt lgkmcnt(0)
	v_pk_mul_f32 v[58:59], v[60:61], v[58:59]
	v_mul_f32_e32 v61, 0x3dcccccd, v66
	ds_bpermute_b32 v60, v146, v54
	v_mul_f32_e32 v67, 0.15915494, v61
	ds_bpermute_b32 v61, v146, v55
	v_cos_f32_e32 v63, v63
	v_sin_f32_e32 v64, v67
	v_sin_f32_e32 v65, v68
	v_cndmask_b32_e64 v59, v59, -v59, s[2:3]
	v_cndmask_b32_e64 v58, v58, -v58, s[2:3]
	v_pk_fma_f32 v[56:57], v[62:63], v[56:57], v[58:59]
	s_waitcnt lgkmcnt(0)
	v_pk_mul_f32 v[60:61], v[64:65], v[60:61]
	v_mul_f32_e32 v63, 0x3c23d70b, v66
	v_mul_f32_e32 v65, 0x3b4f3e39, v66
	v_cos_f32_e32 v58, v67
	v_cos_f32_e32 v59, v68
	ds_bpermute_b32 v62, v146, v52
	v_mul_f32_e32 v67, 0.15915494, v63
	ds_bpermute_b32 v63, v146, v53
	v_mul_f32_e32 v68, 0.15915494, v65
	v_sin_f32_e32 v64, v67
	v_sin_f32_e32 v65, v68
	v_cndmask_b32_e64 v61, v61, -v61, s[2:3]
	v_cndmask_b32_e64 v60, v60, -v60, s[2:3]
	v_pk_fma_f32 v[54:55], v[58:59], v[54:55], v[60:61]
	v_cos_f32_e32 v58, v67
	v_cos_f32_e32 v59, v68
	s_waitcnt lgkmcnt(0)
	v_pk_mul_f32 v[60:61], v[64:65], v[62:63]
	v_mul_f32_e32 v63, 0x3a831270, v66
	v_mul_f32_e32 v65, 0x39a5cb61, v66
	ds_bpermute_b32 v62, v146, v50
	v_mul_f32_e32 v67, 0.15915494, v63
	ds_bpermute_b32 v63, v146, v51
	v_mul_f32_e32 v66, 0.15915494, v65
	v_sin_f32_e32 v64, v67
	v_sin_f32_e32 v65, v66
	v_cndmask_b32_e64 v61, v61, -v61, s[2:3]
	v_cndmask_b32_e64 v60, v60, -v60, s[2:3]
	v_pk_fma_f32 v[52:53], v[58:59], v[52:53], v[60:61]
	v_cos_f32_e32 v58, v67
	v_cos_f32_e32 v59, v66
	s_waitcnt lgkmcnt(0)
	v_pk_mul_f32 v[60:61], v[64:65], v[62:63]
	s_nop 0
	v_cndmask_b32_e64 v61, v61, -v61, s[2:3]
	v_cndmask_b32_e64 v60, v60, -v60, s[2:3]
	v_pk_fma_f32 v[50:51], v[58:59], v[50:51], v[60:61]

.LBB0_664:
	v_mul_f32_e32 v59, v47, v47
	v_fmac_f32_e32 v59, v46, v46
	v_fmac_f32_e32 v59, v48, v48
	v_fmac_f32_e32 v59, v49, v49
	v_fmac_f32_e32 v59, v42, v42
	v_fmac_f32_e32 v59, v43, v43
	v_fmac_f32_e32 v59, v44, v44
	v_fmac_f32_e32 v59, v45, v45
	v_fmac_f32_e32 v59, v38, v38
	v_fmac_f32_e32 v59, v39, v39
	v_fmac_f32_e32 v59, v40, v40
	v_fmac_f32_e32 v59, v41, v41
	v_fmac_f32_e32 v59, v34, v34
	v_fmac_f32_e32 v59, v35, v35
	v_fmac_f32_e32 v59, v36, v36
	v_pk_mul_f32 v[66:67], v[50:51], v[50:51]
	v_fmac_f32_e32 v59, v37, v37
	v_add_f32_e32 v59, v59, v66
	v_pk_mul_f32 v[68:69], v[52:53], v[52:53]
	v_add_f32_e32 v59, v67, v59
	v_add_f32_e32 v59, v68, v59
	v_pk_mul_f32 v[70:71], v[54:55], v[54:55]
	v_add_f32_e32 v59, v69, v59
	v_add_f32_e32 v59, v70, v59
	v_pk_mul_f32 v[72:73], v[56:57], v[56:57]
	v_add_f32_e32 v59, v71, v59
	v_add_f32_e32 v59, v72, v59
	v_add_f32_e32 v59, v73, v59
	v_mov_b32_e32 v61, v59
	s_nop 1
	v_permlane16_swap_b32_e32 v61, v59
	v_mov_b64_e32 v[66:67], s[24:25]
	v_mov_b32_e32 v127, v163
	s_waitcnt lgkmcnt(0)
	v_add_f32_e32 v59, v59, v61
	v_mov_b32_e32 v61, v59
	s_nop 1
	v_permlane32_swap_b32_e32 v61, v59
	s_waitcnt lgkmcnt(0)
	v_add_f32_e32 v59, v59, v61
	v_fmamk_f32 v59, v59, 0x3c2aaaab, v1
	v_mul_f32_e32 v61, 0x4b800000, v59
	v_cmp_gt_f32_e32 vcc, s56, v59
	s_nop 1
	v_cndmask_b32_e32 v59, v59, v61, vcc
	v_rsq_f32_e32 v61, v59
	v_mad_i64_i32 v[58:59], s[30:31], v58, s57, v[66:67]
	v_lshl_add_u64 v[58:59], v[140:141], 1, v[58:59]
	v_mul_f32_e32 v68, 0x45800000, v61
	v_cndmask_b32_e32 v68, v61, v68, vcc
	v_mul_f32_e32 v46, v46, v68
	v_mul_f32_e32 v47, v47, v68
	v_lshl_add_u64 v[66:67], v[58:59], 0, v[126:127]
	v_mul_f32_e32 v48, v48, v68
	v_mul_f32_e32 v49, v49, v68
	v_mul_f32_e32 v42, v42, v68
	v_mul_f32_e32 v43, v43, v68
	v_mul_f32_e32 v44, v44, v68
	v_mul_f32_e32 v45, v45, v68
	v_mul_f32_e32 v38, v38, v68
	v_mul_f32_e32 v39, v39, v68
	v_mul_f32_e32 v40, v40, v68
	v_mul_f32_e32 v41, v41, v68
	v_mul_f32_e32 v34, v34, v68
	v_mul_f32_e32 v35, v35, v68
	v_mul_f32_e32 v36, v36, v68
	v_mul_f32_e32 v37, v37, v68
	s_and_b64 vcc, exec, s[6:7]
	v_mul_f32_e32 v46, v170, v46
	v_mul_f32_e32 v47, v171, v47
	v_mul_f32_e32 v48, v172, v48
	v_mul_f32_e32 v49, v173, v49
	v_cvt_pk_bf16_f32 v46, v46, v47
	v_cvt_pk_bf16_f32 v47, v48, v49
	global_store_dwordx2 v[66:67], v[46:47], off
	v_mul_f32_e32 v42, v174, v42
	v_mul_f32_e32 v43, v175, v43
	v_mul_f32_e32 v44, v176, v44
	v_mul_f32_e32 v45, v177, v45
	v_cvt_pk_bf16_f32 v42, v42, v43
	v_cvt_pk_bf16_f32 v43, v44, v45
	global_store_dwordx2 v[66:67], v[42:43], off offset:32
	v_mul_f32_e32 v38, v178, v38
	v_mul_f32_e32 v39, v179, v39
	v_mul_f32_e32 v40, v180, v40
	v_mul_f32_e32 v41, v41, v181
	v_cvt_pk_bf16_f32 v38, v38, v39
	v_cvt_pk_bf16_f32 v39, v40, v41
	global_store_dwordx2 v[66:67], v[38:39], off offset:64
	v_mul_f32_e32 v34, v34, v182
	v_mul_f32_e32 v35, v35, v183
	v_mul_f32_e32 v36, v36, v184
	v_mul_f32_e32 v37, v37, v185
	v_cvt_pk_bf16_f32 v34, v34, v35
	v_cvt_pk_bf16_f32 v35, v36, v37
	global_store_dwordx2 v[66:67], v[34:35], off offset:96
	s_nop 0
	v_mov_b32_e32 v34, v186
	v_mov_b32_e32 v35, v187
	v_mov_b32_e32 v36, v188
	v_mov_b32_e32 v37, v189
	v_pk_mul_f32 v[34:35], v[68:69], v[34:35] op_sel_hi:[0,1]
	v_pk_mul_f32 v[36:37], v[68:69], v[36:37] op_sel_hi:[0,1]
	v_pk_mul_f32 v[42:43], v[68:69], v[190:191] op_sel_hi:[0,1]
	v_pk_mul_f32 v[44:45], v[68:69], v[192:193] op_sel_hi:[0,1]
	v_pk_mul_f32 v[40:41], v[50:51], v[34:35]
	v_pk_mul_f32 v[38:39], v[52:53], v[36:37]
	v_pk_mul_f32 v[36:37], v[54:55], v[42:43]
	v_pk_mul_f32 v[34:35], v[56:57], v[44:45]
	s_cbranch_vccnz .LBB0_666
	v_add_u32_e32 v42, s60, v60
	v_ashrrev_i32_e32 v43, 6, v42
	v_and_b32_e32 v42, 63, v42
	v_cndmask_b32_e64 v42, v42, v43, s[4:5]
	v_cvt_f32_i32_e32 v50, v42
	ds_bpermute_b32 v42, v146, v40
	ds_bpermute_b32 v43, v146, v41
	v_mul_f32_e32 v45, 0x3ea1e89b, v50
	v_mul_f32_e32 v46, 0.15915494, v50
	v_mul_f32_e32 v47, 0.15915494, v45
	v_sin_f32_e32 v44, v46
	v_sin_f32_e32 v45, v47
	v_mul_f32_e32 v49, 0x3d0186e3, v50
	v_mul_f32_e32 v52, 0.15915494, v49
	v_cos_f32_e32 v46, v46
	s_waitcnt lgkmcnt(0)
	v_pk_mul_f32 v[42:43], v[44:45], v[42:43]
	v_mul_f32_e32 v45, 0x3dcccccd, v50
	ds_bpermute_b32 v44, v146, v38
	v_mul_f32_e32 v51, 0.15915494, v45
	ds_bpermute_b32 v45, v146, v39
	v_cos_f32_e32 v47, v47
	v_sin_f32_e32 v48, v51
	v_sin_f32_e32 v49, v52
	v_cndmask_b32_e64 v43, v43, -v43, s[2:3]
	v_cndmask_b32_e64 v42, v42, -v42, s[2:3]
	v_pk_fma_f32 v[40:41], v[46:47], v[40:41], v[42:43]
	s_waitcnt lgkmcnt(0)
	v_pk_mul_f32 v[44:45], v[48:49], v[44:45]
	v_mul_f32_e32 v47, 0x3c23d70b, v50
	v_mul_f32_e32 v49, 0x3b4f3e39, v50
	v_cos_f32_e32 v42, v51
	v_cos_f32_e32 v43, v52
	ds_bpermute_b32 v46, v146, v36
	v_mul_f32_e32 v51, 0.15915494, v47
	ds_bpermute_b32 v47, v146, v37
	v_mul_f32_e32 v52, 0.15915494, v49
	v_sin_f32_e32 v48, v51
	v_sin_f32_e32 v49, v52
	v_cndmask_b32_e64 v45, v45, -v45, s[2:3]
	v_cndmask_b32_e64 v44, v44, -v44, s[2:3]
	v_pk_fma_f32 v[38:39], v[42:43], v[38:39], v[44:45]
	v_cos_f32_e32 v42, v51
	v_cos_f32_e32 v43, v52
	s_waitcnt lgkmcnt(0)
	v_pk_mul_f32 v[44:45], v[48:49], v[46:47]
	v_mul_f32_e32 v47, 0x3a831270, v50
	v_mul_f32_e32 v49, 0x39a5cb61, v50
	ds_bpermute_b32 v46, v146, v34
	v_mul_f32_e32 v51, 0.15915494, v47
	ds_bpermute_b32 v47, v146, v35
	v_mul_f32_e32 v50, 0.15915494, v49
	v_sin_f32_e32 v48, v51
	v_sin_f32_e32 v49, v50
	v_cndmask_b32_e64 v45, v45, -v45, s[2:3]
	v_cndmask_b32_e64 v44, v44, -v44, s[2:3]
	v_pk_fma_f32 v[36:37], v[42:43], v[36:37], v[44:45]
	v_cos_f32_e32 v42, v51
	v_cos_f32_e32 v43, v50
	s_waitcnt lgkmcnt(0)
	v_pk_mul_f32 v[44:45], v[48:49], v[46:47]
	s_nop 0
	v_cndmask_b32_e64 v45, v45, -v45, s[2:3]
	v_cndmask_b32_e64 v44, v44, -v44, s[2:3]
	v_pk_fma_f32 v[34:35], v[42:43], v[34:35], v[44:45]

.LBB0_672:
	v_mul_f32_e32 v43, v31, v31
	v_fmac_f32_e32 v43, v30, v30
	v_fmac_f32_e32 v43, v32, v32
	v_fmac_f32_e32 v43, v33, v33
	v_fmac_f32_e32 v43, v26, v26
	v_fmac_f32_e32 v43, v27, v27
	v_fmac_f32_e32 v43, v28, v28
	v_fmac_f32_e32 v43, v29, v29
	v_fmac_f32_e32 v43, v22, v22
	v_fmac_f32_e32 v43, v23, v23
	v_fmac_f32_e32 v43, v24, v24
	v_fmac_f32_e32 v43, v25, v25
	v_fmac_f32_e32 v43, v18, v18
	v_fmac_f32_e32 v43, v19, v19
	v_fmac_f32_e32 v43, v20, v20
	v_pk_mul_f32 v[50:51], v[34:35], v[34:35]
	v_fmac_f32_e32 v43, v21, v21
	v_add_f32_e32 v43, v43, v50
	v_pk_mul_f32 v[52:53], v[36:37], v[36:37]
	v_add_f32_e32 v43, v51, v43
	v_add_f32_e32 v43, v52, v43
	v_pk_mul_f32 v[54:55], v[38:39], v[38:39]
	v_add_f32_e32 v43, v53, v43
	v_add_f32_e32 v43, v54, v43
	v_pk_mul_f32 v[56:57], v[40:41], v[40:41]
	v_add_f32_e32 v43, v55, v43
	v_add_f32_e32 v43, v56, v43
	v_add_f32_e32 v43, v57, v43
	v_mov_b32_e32 v45, v43
	s_nop 1
	v_permlane16_swap_b32_e32 v45, v43
	v_mov_b64_e32 v[50:51], s[24:25]
	v_mov_b32_e32 v127, v163
	s_waitcnt lgkmcnt(0)
	v_add_f32_e32 v43, v43, v45
	v_mov_b32_e32 v45, v43
	s_nop 1
	v_permlane32_swap_b32_e32 v45, v43
	s_waitcnt lgkmcnt(0)
	v_add_f32_e32 v43, v43, v45
	v_fmamk_f32 v43, v43, 0x3c2aaaab, v1
	v_mul_f32_e32 v45, 0x4b800000, v43
	v_cmp_gt_f32_e32 vcc, s56, v43
	s_nop 1
	v_cndmask_b32_e32 v43, v43, v45, vcc
	v_rsq_f32_e32 v45, v43
	v_mad_i64_i32 v[42:43], s[30:31], v42, s57, v[50:51]
	v_lshl_add_u64 v[42:43], v[140:141], 1, v[42:43]
	v_mul_f32_e32 v52, 0x45800000, v45
	v_cndmask_b32_e32 v52, v45, v52, vcc
	v_mul_f32_e32 v30, v30, v52
	v_mul_f32_e32 v31, v31, v52
	v_lshl_add_u64 v[50:51], v[42:43], 0, v[126:127]
	v_mul_f32_e32 v32, v32, v52
	v_mul_f32_e32 v33, v33, v52
	v_mul_f32_e32 v26, v26, v52
	v_mul_f32_e32 v27, v27, v52
	v_mul_f32_e32 v28, v28, v52
	v_mul_f32_e32 v29, v29, v52
	v_mul_f32_e32 v22, v22, v52
	v_mul_f32_e32 v23, v23, v52
	v_mul_f32_e32 v24, v24, v52
	v_mul_f32_e32 v25, v25, v52
	v_mul_f32_e32 v18, v18, v52
	v_mul_f32_e32 v19, v19, v52
	v_mul_f32_e32 v20, v20, v52
	v_mul_f32_e32 v21, v21, v52
	s_and_b64 vcc, exec, s[6:7]
	v_mul_f32_e32 v30, v170, v30
	v_mul_f32_e32 v31, v171, v31
	v_mul_f32_e32 v32, v172, v32
	v_mul_f32_e32 v33, v173, v33
	v_cvt_pk_bf16_f32 v30, v30, v31
	v_cvt_pk_bf16_f32 v31, v32, v33
	global_store_dwordx2 v[50:51], v[30:31], off
	v_mul_f32_e32 v26, v174, v26
	v_mul_f32_e32 v27, v175, v27
	v_mul_f32_e32 v28, v176, v28
	v_mul_f32_e32 v29, v177, v29
	v_cvt_pk_bf16_f32 v26, v26, v27
	v_cvt_pk_bf16_f32 v27, v28, v29
	global_store_dwordx2 v[50:51], v[26:27], off offset:32
	v_mul_f32_e32 v22, v178, v22
	v_mul_f32_e32 v23, v179, v23
	v_mul_f32_e32 v24, v180, v24
	v_mul_f32_e32 v25, v25, v181
	v_cvt_pk_bf16_f32 v22, v22, v23
	v_cvt_pk_bf16_f32 v23, v24, v25
	global_store_dwordx2 v[50:51], v[22:23], off offset:64
	v_mul_f32_e32 v18, v18, v182
	v_mul_f32_e32 v19, v19, v183
	v_mul_f32_e32 v20, v20, v184
	v_mul_f32_e32 v21, v21, v185
	v_cvt_pk_bf16_f32 v18, v18, v19
	v_cvt_pk_bf16_f32 v19, v20, v21
	global_store_dwordx2 v[50:51], v[18:19], off offset:96
	s_nop 0
	v_mov_b32_e32 v18, v186
	v_mov_b32_e32 v19, v187
	v_mov_b32_e32 v20, v188
	v_mov_b32_e32 v21, v189
	v_pk_mul_f32 v[18:19], v[52:53], v[18:19] op_sel_hi:[0,1]
	v_pk_mul_f32 v[20:21], v[52:53], v[20:21] op_sel_hi:[0,1]
	v_pk_mul_f32 v[26:27], v[52:53], v[190:191] op_sel_hi:[0,1]
	v_pk_mul_f32 v[28:29], v[52:53], v[192:193] op_sel_hi:[0,1]
	v_pk_mul_f32 v[24:25], v[34:35], v[18:19]
	v_pk_mul_f32 v[22:23], v[36:37], v[20:21]
	v_pk_mul_f32 v[20:21], v[38:39], v[26:27]
	v_pk_mul_f32 v[18:19], v[40:41], v[28:29]
	s_cbranch_vccnz .LBB0_674
	v_add_u32_e32 v26, s60, v44
	v_ashrrev_i32_e32 v27, 6, v26
	v_and_b32_e32 v26, 63, v26
	v_cndmask_b32_e64 v26, v26, v27, s[4:5]
	v_cvt_f32_i32_e32 v34, v26
	ds_bpermute_b32 v26, v146, v24
	ds_bpermute_b32 v27, v146, v25
	v_mul_f32_e32 v29, 0x3ea1e89b, v34
	v_mul_f32_e32 v30, 0.15915494, v34
	v_mul_f32_e32 v31, 0.15915494, v29
	v_sin_f32_e32 v28, v30
	v_sin_f32_e32 v29, v31
	v_mul_f32_e32 v33, 0x3d0186e3, v34
	v_mul_f32_e32 v36, 0.15915494, v33
	v_cos_f32_e32 v30, v30
	s_waitcnt lgkmcnt(0)
	v_pk_mul_f32 v[26:27], v[28:29], v[26:27]
	v_mul_f32_e32 v29, 0x3dcccccd, v34
	ds_bpermute_b32 v28, v146, v22
	v_mul_f32_e32 v35, 0.15915494, v29
	ds_bpermute_b32 v29, v146, v23
	v_cos_f32_e32 v31, v31
	v_sin_f32_e32 v32, v35
	v_sin_f32_e32 v33, v36
	v_cndmask_b32_e64 v27, v27, -v27, s[2:3]
	v_cndmask_b32_e64 v26, v26, -v26, s[2:3]
	v_pk_fma_f32 v[24:25], v[30:31], v[24:25], v[26:27]
	s_waitcnt lgkmcnt(0)
	v_pk_mul_f32 v[28:29], v[32:33], v[28:29]
	v_mul_f32_e32 v31, 0x3c23d70b, v34
	v_mul_f32_e32 v33, 0x3b4f3e39, v34
	v_cos_f32_e32 v26, v35
	v_cos_f32_e32 v27, v36
	ds_bpermute_b32 v30, v146, v20
	v_mul_f32_e32 v35, 0.15915494, v31
	ds_bpermute_b32 v31, v146, v21
	v_mul_f32_e32 v36, 0.15915494, v33
	v_sin_f32_e32 v32, v35
	v_sin_f32_e32 v33, v36
	v_cndmask_b32_e64 v29, v29, -v29, s[2:3]
	v_cndmask_b32_e64 v28, v28, -v28, s[2:3]
	v_pk_fma_f32 v[22:23], v[26:27], v[22:23], v[28:29]
	v_cos_f32_e32 v26, v35
	v_cos_f32_e32 v27, v36
	s_waitcnt lgkmcnt(0)
	v_pk_mul_f32 v[28:29], v[32:33], v[30:31]
	v_mul_f32_e32 v31, 0x3a831270, v34
	v_mul_f32_e32 v33, 0x39a5cb61, v34
	ds_bpermute_b32 v30, v146, v18
	v_mul_f32_e32 v35, 0.15915494, v31
	ds_bpermute_b32 v31, v146, v19
	v_mul_f32_e32 v34, 0.15915494, v33
	v_sin_f32_e32 v32, v35
	v_sin_f32_e32 v33, v34
	v_cndmask_b32_e64 v29, v29, -v29, s[2:3]
	v_cndmask_b32_e64 v28, v28, -v28, s[2:3]
	v_pk_fma_f32 v[20:21], v[26:27], v[20:21], v[28:29]
	v_cos_f32_e32 v26, v35
	v_cos_f32_e32 v27, v34
	s_waitcnt lgkmcnt(0)
	v_pk_mul_f32 v[28:29], v[32:33], v[30:31]
	s_nop 0
	v_cndmask_b32_e64 v29, v29, -v29, s[2:3]
	v_cndmask_b32_e64 v28, v28, -v28, s[2:3]
	v_pk_fma_f32 v[18:19], v[26:27], v[18:19], v[28:29]

.LBB0_680:
	v_mul_f32_e32 v27, v15, v15
	v_fmac_f32_e32 v27, v14, v14
	v_fmac_f32_e32 v27, v16, v16
	v_fmac_f32_e32 v27, v17, v17
	v_fmac_f32_e32 v27, v10, v10
	v_fmac_f32_e32 v27, v11, v11
	v_fmac_f32_e32 v27, v12, v12
	v_fmac_f32_e32 v27, v13, v13
	v_fmac_f32_e32 v27, v6, v6
	v_fmac_f32_e32 v27, v7, v7
	v_fmac_f32_e32 v27, v8, v8
	v_fmac_f32_e32 v27, v9, v9
	v_fmac_f32_e32 v27, v2, v2
	v_fmac_f32_e32 v27, v3, v3
	v_fmac_f32_e32 v27, v4, v4
	v_pk_mul_f32 v[34:35], v[18:19], v[18:19]
	v_fmac_f32_e32 v27, v5, v5
	v_add_f32_e32 v27, v27, v34
	v_pk_mul_f32 v[36:37], v[20:21], v[20:21]
	v_add_f32_e32 v27, v35, v27
	v_add_f32_e32 v27, v36, v27
	v_pk_mul_f32 v[38:39], v[22:23], v[22:23]
	v_add_f32_e32 v27, v37, v27
	v_add_f32_e32 v27, v38, v27
	v_pk_mul_f32 v[40:41], v[24:25], v[24:25]
	v_add_f32_e32 v27, v39, v27
	v_add_f32_e32 v27, v40, v27
	v_add_f32_e32 v27, v41, v27
	v_mov_b32_e32 v29, v27
	s_nop 1
	v_permlane16_swap_b32_e32 v29, v27
	v_mov_b64_e32 v[34:35], s[24:25]
	v_mov_b32_e32 v127, v163
	s_waitcnt lgkmcnt(0)
	v_add_f32_e32 v27, v27, v29
	v_mov_b32_e32 v29, v27
	s_nop 1
	v_permlane32_swap_b32_e32 v29, v27
	s_waitcnt lgkmcnt(0)
	v_add_f32_e32 v27, v27, v29
	v_fmamk_f32 v27, v27, 0x3c2aaaab, v1
	v_mul_f32_e32 v29, 0x4b800000, v27
	v_cmp_gt_f32_e32 vcc, s56, v27
	s_nop 1
	v_cndmask_b32_e32 v27, v27, v29, vcc
	v_rsq_f32_e32 v29, v27
	v_mad_i64_i32 v[26:27], s[30:31], v26, s57, v[34:35]
	v_lshl_add_u64 v[26:27], v[140:141], 1, v[26:27]
	v_mul_f32_e32 v36, 0x45800000, v29
	v_cndmask_b32_e32 v36, v29, v36, vcc
	v_mul_f32_e32 v14, v14, v36
	v_mul_f32_e32 v15, v15, v36
	v_lshl_add_u64 v[34:35], v[26:27], 0, v[126:127]
	v_mul_f32_e32 v16, v16, v36
	v_mul_f32_e32 v17, v17, v36
	v_mul_f32_e32 v10, v10, v36
	v_mul_f32_e32 v11, v11, v36
	v_mul_f32_e32 v12, v12, v36
	v_mul_f32_e32 v13, v13, v36
	v_mul_f32_e32 v6, v6, v36
	v_mul_f32_e32 v7, v7, v36
	v_mul_f32_e32 v8, v8, v36
	v_mul_f32_e32 v9, v9, v36
	v_mul_f32_e32 v2, v2, v36
	v_mul_f32_e32 v3, v3, v36
	v_mul_f32_e32 v4, v4, v36
	v_mul_f32_e32 v5, v5, v36
	s_and_b64 vcc, exec, s[6:7]
	v_mul_f32_e32 v14, v170, v14
	v_mul_f32_e32 v15, v171, v15
	v_mul_f32_e32 v16, v172, v16
	v_mul_f32_e32 v17, v173, v17
	v_cvt_pk_bf16_f32 v14, v14, v15
	v_cvt_pk_bf16_f32 v15, v16, v17
	global_store_dwordx2 v[34:35], v[14:15], off
	v_mul_f32_e32 v10, v174, v10
	v_mul_f32_e32 v11, v175, v11
	v_mul_f32_e32 v12, v176, v12
	v_mul_f32_e32 v13, v177, v13
	v_cvt_pk_bf16_f32 v10, v10, v11
	v_cvt_pk_bf16_f32 v11, v12, v13
	global_store_dwordx2 v[34:35], v[10:11], off offset:32
	v_mul_f32_e32 v6, v178, v6
	v_mul_f32_e32 v7, v179, v7
	v_mul_f32_e32 v8, v180, v8
	v_mul_f32_e32 v9, v9, v181
	v_cvt_pk_bf16_f32 v6, v6, v7
	v_cvt_pk_bf16_f32 v7, v8, v9
	global_store_dwordx2 v[34:35], v[6:7], off offset:64
	v_mul_f32_e32 v2, v2, v182
	v_mul_f32_e32 v3, v3, v183
	v_mul_f32_e32 v4, v4, v184
	v_mul_f32_e32 v5, v5, v185
	v_cvt_pk_bf16_f32 v2, v2, v3
	v_cvt_pk_bf16_f32 v3, v4, v5
	global_store_dwordx2 v[34:35], v[2:3], off offset:96
	s_nop 0
	v_mov_b32_e32 v2, v186
	v_mov_b32_e32 v3, v187
	v_mov_b32_e32 v4, v188
	v_mov_b32_e32 v5, v189
	v_pk_mul_f32 v[2:3], v[36:37], v[2:3] op_sel_hi:[0,1]
	v_pk_mul_f32 v[4:5], v[36:37], v[4:5] op_sel_hi:[0,1]
	v_pk_mul_f32 v[10:11], v[36:37], v[190:191] op_sel_hi:[0,1]
	v_pk_mul_f32 v[12:13], v[36:37], v[192:193] op_sel_hi:[0,1]
	v_pk_mul_f32 v[8:9], v[18:19], v[2:3]
	v_pk_mul_f32 v[6:7], v[20:21], v[4:5]
	v_pk_mul_f32 v[4:5], v[22:23], v[10:11]
	v_pk_mul_f32 v[2:3], v[24:25], v[12:13]
	s_cbranch_vccnz .LBB0_682
	v_add_u32_e32 v10, s60, v28
	v_ashrrev_i32_e32 v11, 6, v10
	v_and_b32_e32 v10, 63, v10
	v_cndmask_b32_e64 v10, v10, v11, s[4:5]
	v_cvt_f32_i32_e32 v18, v10
	ds_bpermute_b32 v10, v146, v8
	ds_bpermute_b32 v11, v146, v9
	v_mul_f32_e32 v13, 0x3ea1e89b, v18
	v_mul_f32_e32 v14, 0.15915494, v18
	v_mul_f32_e32 v15, 0.15915494, v13
	v_sin_f32_e32 v12, v14
	v_sin_f32_e32 v13, v15
	v_mul_f32_e32 v17, 0x3d0186e3, v18
	v_mul_f32_e32 v20, 0.15915494, v17
	v_cos_f32_e32 v14, v14
	s_waitcnt lgkmcnt(0)
	v_pk_mul_f32 v[10:11], v[12:13], v[10:11]
	v_mul_f32_e32 v13, 0x3dcccccd, v18
	ds_bpermute_b32 v12, v146, v6
	v_mul_f32_e32 v19, 0.15915494, v13
	ds_bpermute_b32 v13, v146, v7
	v_cos_f32_e32 v15, v15
	v_sin_f32_e32 v16, v19
	v_sin_f32_e32 v17, v20
	v_cndmask_b32_e64 v11, v11, -v11, s[2:3]
	v_cndmask_b32_e64 v10, v10, -v10, s[2:3]
	v_pk_fma_f32 v[8:9], v[14:15], v[8:9], v[10:11]
	s_waitcnt lgkmcnt(0)
	v_pk_mul_f32 v[12:13], v[16:17], v[12:13]
	v_mul_f32_e32 v15, 0x3c23d70b, v18
	v_mul_f32_e32 v17, 0x3b4f3e39, v18
	v_cos_f32_e32 v10, v19
	v_cos_f32_e32 v11, v20
	ds_bpermute_b32 v14, v146, v4
	v_mul_f32_e32 v19, 0.15915494, v15
	ds_bpermute_b32 v15, v146, v5
	v_mul_f32_e32 v20, 0.15915494, v17
	v_sin_f32_e32 v16, v19
	v_sin_f32_e32 v17, v20
	v_cndmask_b32_e64 v13, v13, -v13, s[2:3]
	v_cndmask_b32_e64 v12, v12, -v12, s[2:3]
	v_pk_fma_f32 v[6:7], v[10:11], v[6:7], v[12:13]
	v_cos_f32_e32 v10, v19
	v_cos_f32_e32 v11, v20
	s_waitcnt lgkmcnt(0)
	v_pk_mul_f32 v[12:13], v[16:17], v[14:15]
	v_mul_f32_e32 v15, 0x3a831270, v18
	v_mul_f32_e32 v17, 0x39a5cb61, v18
	ds_bpermute_b32 v14, v146, v2
	v_mul_f32_e32 v19, 0.15915494, v15
	ds_bpermute_b32 v15, v146, v3
	v_mul_f32_e32 v18, 0.15915494, v17
	v_sin_f32_e32 v16, v19
	v_sin_f32_e32 v17, v18
	v_cndmask_b32_e64 v13, v13, -v13, s[2:3]
	v_cndmask_b32_e64 v12, v12, -v12, s[2:3]
	v_pk_fma_f32 v[4:5], v[10:11], v[4:5], v[12:13]
	v_cos_f32_e32 v10, v19
	v_cos_f32_e32 v11, v18
	s_waitcnt lgkmcnt(0)
	v_pk_mul_f32 v[12:13], v[16:17], v[14:15]
	s_nop 0
	v_cndmask_b32_e64 v13, v13, -v13, s[2:3]
	v_cndmask_b32_e64 v12, v12, -v12, s[2:3]
	v_pk_fma_f32 v[2:3], v[10:11], v[2:3], v[12:13]

.LBB0_833:
	v_mul_f32_e32 v41, v41, v62
	v_mul_f32_e32 v40, v40, v61
	v_mul_f32_e32 v39, v39, v60
	v_mul_f32_e32 v38, v38, v59
	v_mul_f32_e32 v62, 0x3e000000, v41
	v_mul_f32_e32 v61, 0x3e000000, v40
	v_mul_f32_e32 v60, 0x3e000000, v39
	v_mul_f32_e32 v59, 0x3e000000, v38
	ds_read2_b64 v[38:41], v53 offset1:2
	v_mul_f32_e32 v36, v36, v56
	v_mul_f32_e32 v42, v42, v64
	v_mul_f32_e32 v37, v37, v57
	v_mul_f32_e32 v36, 0x3e000000, v36
	v_mul_f32_e32 v47, v47, v90
	v_mul_f32_e32 v43, v43, v66
	v_mul_f32_e32 v42, 0x3e000000, v42
	v_mul_f32_e32 v37, 0x3e000000, v37
	v_cvt_pk_bf16_f32 v90, v36, v37
	v_mul_f32_e32 v36, v46, v67
	v_mul_f32_e32 v50, v50, v93
	v_mul_f32_e32 v43, 0x3e000000, v43
	v_cvt_pk_bf16_f32 v93, v42, v43
	v_mul_f32_e32 v42, 0x3e000000, v36
	v_mul_f32_e32 v36, v45, v65
	v_mul_f32_e32 v49, v49, v92
	v_mul_f32_e32 v48, v48, v91
	v_cvt_pk_bf16_f32 v91, v59, v60
	v_cvt_pk_bf16_f32 v92, v61, v62
	v_add_u32_e32 v56, 0x2000, v53
	s_waitcnt lgkmcnt(0)
	v_mfma_f32_32x32x16_bf16 v[20:35], v[38:41], v[90:93], v[20:35]
	v_mul_f32_e32 v40, 0x3e000000, v36
	ds_read2_b64 v[36:39], v53 offset0:4 offset1:6
	ds_read2_b64 v[94:97], v56 offset0:32 offset1:34
	v_mul_f32_e32 v43, v44, v63
	v_mul_f32_e32 v41, 0x3e000000, v47
	v_mul_f32_e32 v43, 0x3e000000, v43
	v_mul_f32_e32 v44, v51, v58
	v_mul_f32_e32 v50, 0x3e000000, v50
	v_mul_f32_e32 v49, 0x3e000000, v49
	v_mul_f32_e32 v48, 0x3e000000, v48
	v_mul_f32_e32 v44, 0x3e000000, v44
	v_cvt_pk_bf16_f32 v40, v43, v40
	v_cvt_pk_bf16_f32 v41, v42, v41
	v_cvt_pk_bf16_f32 v42, v48, v49
	v_cvt_pk_bf16_f32 v43, v50, v44
	s_waitcnt lgkmcnt(0)
	v_mfma_f32_32x32x16_bf16 v[4:19], v[94:97], v[90:93], v[4:19]
	s_sub_i32 s4, s4, 32
	v_add_u32_e32 v53, 64, v53
	v_add_u32_e32 v85, 0x1200, v85
	s_cmpk_lg_i32 s4, 0xff80
	v_add_u32_e32 v55, 32, v55
	v_mfma_f32_32x32x16_bf16 v[20:35], v[36:39], v[40:43], v[20:35]
	ds_read2_b64 v[36:39], v56 offset0:36 offset1:38
	s_waitcnt lgkmcnt(0)
	v_mfma_f32_32x32x16_bf16 v[4:19], v[36:39], v[40:43], v[4:19]
	s_cbranch_scc0 .LBB0_776
.LBB0_834:
	ds_read_b128 v[36:39], v85
	ds_read_b128 v[56:59], v85 offset:32
	s_waitcnt lgkmcnt(1)
	v_mfma_f32_32x32x16_bf16 v[36:51], v[36:39], v[68:71], 0
	s_waitcnt lgkmcnt(0)
	v_mfma_f32_32x32x16_bf16 v[36:51], v[56:59], v[72:75], v[36:51]
	ds_read_b128 v[56:59], v85 offset:64
	ds_read_b128 v[60:63], v85 offset:96
	s_waitcnt lgkmcnt(1)
	v_mfma_f32_32x32x16_bf16 v[36:51], v[56:59], v[76:79], v[36:51]
	v_add_u32_e32 v58, s4, v54
	s_waitcnt lgkmcnt(0)
	v_mfma_f32_32x32x16_bf16 v[36:51], v[60:63], v[80:83], v[36:51]
	v_cmp_gt_i32_e32 vcc, 1, v58
	v_add_u32_e32 v227, v52, v55
	s_nop 0
	v_cndmask_b32_e32 v226, v88, v89, vcc
	v_cndmask_b32_e32 v227, v58, v227, vcc
	v_cmp_ne_u32_e32 vcc, 0, v58
	v_cvt_f32_u32_e32 v227, v227
	v_mul_f32_e32 v227, v226, v227
	v_exp_f32_e32 v227, v227
	s_nop 0
	v_cndmask_b32_e32 v56, 2.0, v227, vcc
	v_add_u32_e32 v59, -1, v58
	v_cmp_gt_i32_e32 vcc, 1, v59
	v_add3_u32 v227, v52, v55, 1
	s_nop 0
	v_cndmask_b32_e32 v226, v88, v89, vcc
	v_cndmask_b32_e32 v227, v59, v227, vcc
	v_cmp_ne_u32_e32 vcc, 0, v59
	v_cvt_f32_u32_e32 v227, v227
	v_mul_f32_e32 v227, v226, v227
	v_exp_f32_e32 v227, v227
	s_nop 0
	v_cndmask_b32_e32 v57, 2.0, v227, vcc
	v_add_u32_e32 v60, -2, v58
	v_cmp_gt_i32_e32 vcc, 1, v60
	v_add3_u32 v227, v52, v55, 2
	s_nop 0
	v_cndmask_b32_e32 v226, v88, v89, vcc
	v_cndmask_b32_e32 v227, v60, v227, vcc
	v_cmp_ne_u32_e32 vcc, 0, v60
	v_cvt_f32_u32_e32 v227, v227
	v_mul_f32_e32 v227, v226, v227
	v_exp_f32_e32 v227, v227
	s_nop 0
	v_cndmask_b32_e32 v59, 2.0, v227, vcc
	v_add_u32_e32 v61, -3, v58
	v_cmp_gt_i32_e32 vcc, 1, v61
	v_add3_u32 v227, v52, v55, 3
	s_nop 0
	v_cndmask_b32_e32 v226, v88, v89, vcc
	v_cndmask_b32_e32 v227, v61, v227, vcc
	v_cmp_ne_u32_e32 vcc, 0, v61
	v_cvt_f32_u32_e32 v227, v227
	v_mul_f32_e32 v227, v226, v227
	v_exp_f32_e32 v227, v227
	s_nop 0
	v_cndmask_b32_e32 v60, 2.0, v227, vcc
	v_add_u32_e32 v62, -8, v58
	v_cmp_gt_i32_e32 vcc, 1, v62
	v_add3_u32 v227, v52, v55, 8
	s_nop 0
	v_cndmask_b32_e32 v226, v88, v89, vcc
	v_cndmask_b32_e32 v227, v62, v227, vcc
	v_cmp_ne_u32_e32 vcc, 0, v62
	v_cvt_f32_u32_e32 v227, v227
	v_mul_f32_e32 v227, v226, v227
	v_exp_f32_e32 v227, v227
	s_nop 0
	v_cndmask_b32_e32 v61, 2.0, v227, vcc
	v_add_u32_e32 v63, -9, v58
	v_cmp_gt_i32_e32 vcc, 1, v63
	v_add3_u32 v227, v52, v55, 9
	s_nop 0
	v_cndmask_b32_e32 v226, v88, v89, vcc
	v_cndmask_b32_e32 v227, v63, v227, vcc
	v_cmp_ne_u32_e32 vcc, 0, v63
	v_cvt_f32_u32_e32 v227, v227
	v_mul_f32_e32 v227, v226, v227
	v_exp_f32_e32 v227, v227
	s_nop 0
	v_cndmask_b32_e32 v62, 2.0, v227, vcc
	v_add_u32_e32 v63, -10, v58
	v_cmp_gt_i32_e32 vcc, 1, v63
	v_add3_u32 v227, v52, v55, 10
	s_nop 0
	v_cndmask_b32_e32 v226, v88, v89, vcc
	v_cndmask_b32_e32 v227, v63, v227, vcc
	v_cmp_ne_u32_e32 vcc, 0, v63
	v_cvt_f32_u32_e32 v227, v227
	v_mul_f32_e32 v227, v226, v227
	v_exp_f32_e32 v227, v227
	s_nop 0
	v_cndmask_b32_e32 v64, 2.0, v227, vcc
	v_add_u32_e32 v63, -11, v58
	v_cmp_gt_i32_e32 vcc, 1, v63
	v_add3_u32 v227, v52, v55, 11
	s_nop 0
	v_cndmask_b32_e32 v226, v88, v89, vcc
	v_cndmask_b32_e32 v227, v63, v227, vcc
	v_cmp_ne_u32_e32 vcc, 0, v63
	v_cvt_f32_u32_e32 v227, v227
	v_mul_f32_e32 v227, v226, v227
	v_exp_f32_e32 v227, v227
	s_nop 0
	v_cndmask_b32_e32 v66, 2.0, v227, vcc
	v_add_u32_e32 v65, -16, v58
	v_cmp_gt_i32_e32 vcc, 1, v65
	v_add3_u32 v227, v52, v55, 16
	s_nop 0
	v_cndmask_b32_e32 v226, v88, v89, vcc
	v_cndmask_b32_e32 v227, v65, v227, vcc
	v_cmp_ne_u32_e32 vcc, 0, v65
	v_cvt_f32_u32_e32 v227, v227
	v_mul_f32_e32 v227, v226, v227
	v_exp_f32_e32 v227, v227
	s_nop 0
	v_cndmask_b32_e32 v63, 2.0, v227, vcc
	v_subrev_u32_e32 v67, 17, v58
	v_cmp_gt_i32_e32 vcc, 1, v67
	v_add3_u32 v227, v52, v55, 17
	s_nop 0
	v_cndmask_b32_e32 v226, v88, v89, vcc
	v_cndmask_b32_e32 v227, v67, v227, vcc
	v_cmp_ne_u32_e32 vcc, 0, v67
	v_cvt_f32_u32_e32 v227, v227
	v_mul_f32_e32 v227, v226, v227
	v_exp_f32_e32 v227, v227
	s_nop 0
	v_cndmask_b32_e32 v65, 2.0, v227, vcc
	v_subrev_u32_e32 v90, 18, v58
	v_cmp_gt_i32_e32 vcc, 1, v90
	v_add3_u32 v227, v52, v55, 18
	s_nop 0
	v_cndmask_b32_e32 v226, v88, v89, vcc
	v_cndmask_b32_e32 v227, v90, v227, vcc
	v_cmp_ne_u32_e32 vcc, 0, v90
	v_cvt_f32_u32_e32 v227, v227
	v_mul_f32_e32 v227, v226, v227
	v_exp_f32_e32 v227, v227
	s_nop 0
	v_cndmask_b32_e32 v67, 2.0, v227, vcc
	v_subrev_u32_e32 v91, 19, v58
	v_cmp_gt_i32_e32 vcc, 1, v91
	v_add3_u32 v227, v52, v55, 19
	s_nop 0
	v_cndmask_b32_e32 v226, v88, v89, vcc
	v_cndmask_b32_e32 v227, v91, v227, vcc
	v_cmp_ne_u32_e32 vcc, 0, v91
	v_cvt_f32_u32_e32 v227, v227
	v_mul_f32_e32 v227, v226, v227
	v_exp_f32_e32 v227, v227
	s_nop 0
	v_cndmask_b32_e32 v90, 2.0, v227, vcc
	v_subrev_u32_e32 v92, 24, v58
	v_cmp_gt_i32_e32 vcc, 1, v92
	v_add3_u32 v227, v52, v55, 24
	s_nop 0
	v_cndmask_b32_e32 v226, v88, v89, vcc
	v_cndmask_b32_e32 v227, v92, v227, vcc
	v_cmp_ne_u32_e32 vcc, 0, v92
	v_cvt_f32_u32_e32 v227, v227
	v_mul_f32_e32 v227, v226, v227
	v_exp_f32_e32 v227, v227
	s_nop 0
	v_cndmask_b32_e32 v91, 2.0, v227, vcc
	v_subrev_u32_e32 v93, 25, v58
	v_cmp_gt_i32_e32 vcc, 1, v93
	v_add3_u32 v227, v52, v55, 25
	s_nop 0
	v_cndmask_b32_e32 v226, v88, v89, vcc
	v_cndmask_b32_e32 v227, v93, v227, vcc
	v_cmp_ne_u32_e32 vcc, 0, v93
	v_cvt_f32_u32_e32 v227, v227
	v_mul_f32_e32 v227, v226, v227
	v_exp_f32_e32 v227, v227
	s_nop 0
	v_cndmask_b32_e32 v92, 2.0, v227, vcc
	v_subrev_u32_e32 v94, 26, v58
	v_cmp_gt_i32_e32 vcc, 1, v94
	v_add3_u32 v227, v52, v55, 26
	s_nop 0
	v_cndmask_b32_e32 v226, v88, v89, vcc
	v_cndmask_b32_e32 v227, v94, v227, vcc
	v_cmp_ne_u32_e32 vcc, 0, v94
	v_cvt_f32_u32_e32 v227, v227
	v_mul_f32_e32 v227, v226, v227
	v_exp_f32_e32 v227, v227
	s_nop 0
	v_cndmask_b32_e32 v93, 2.0, v227, vcc
	v_subrev_u32_e32 v94, 27, v58
	v_cmp_gt_i32_e32 vcc, 1, v94
	v_add3_u32 v227, v52, v55, 27
	s_nop 0
	v_cndmask_b32_e32 v226, v88, v89, vcc
	v_cndmask_b32_e32 v227, v94, v227, vcc
	v_cmp_ne_u32_e32 vcc, 0, v94
	v_cvt_f32_u32_e32 v227, v227
	v_mul_f32_e32 v227, v226, v227
	v_exp_f32_e32 v227, v227
	s_nop 0
	v_cndmask_b32_e32 v58, 2.0, v227, vcc
	s_branch .LBB0_833

.LBB0_1664:
	v_mov_b32_e32 v62, v0
	s_load_dwordx4 s[4:7], s[16:17], 0x98
	v_and_b32_e32 v8, 3, v1
	v_lshlrev_b32_e32 v2, 2, v8
	v_and_b32_e32 v7, 3, v49
	s_waitcnt lgkmcnt(0)
	global_load_dword v6, v2, s[4:5] offset:16
	s_nop 0
	global_load_dword v2, v2, s[6:7] offset:16
	v_lshlrev_b32_e32 v232, 3, v0
	v_and_b32_e32 v232, 56, v232
	v_lshlrev_b32_e32 v232, 1, v232
	v_and_b32_e32 v233, 3, v1
	v_lshl_or_b32 v232, v233, 7, v232
	v_mov_b32_e32 v233, 0
	v_lshl_add_u64 v[234:235], s[22:23], 0, v[232:233]
	v_bfe_u32 v232, v0, 3, 5
	v_ashrrev_i32_e32 v233, 2, v1
	v_lshl_or_b32 v232, v233, 7, v232
	v_mad_i64_i32 v[234:235], s[2:3], v232, s58, v[234:235]
	global_load_dwordx4 v[200:203], v[234:235], off offset:2880
	global_load_dwordx4 v[204:207], v[234:235], off offset:3392
	v_add_co_u32_e32 v234, vcc, 0x22800, v234
	s_nop 1
	v_addc_co_u32_e32 v235, vcc, 0, v235, vcc
	global_load_dwordx4 v[208:211], v[234:235], off offset:2880
	global_load_dwordx4 v[212:215], v[234:235], off offset:3392
	v_add_co_u32_e32 v234, vcc, 0x22800, v234
	s_nop 1
	v_addc_co_u32_e32 v235, vcc, 0, v235, vcc
	global_load_dwordx4 v[216:219], v[234:235], off offset:2880
	global_load_dwordx4 v[220:223], v[234:235], off offset:3392
	v_add_co_u32_e32 v234, vcc, 0x22800, v234
	s_nop 1
	v_addc_co_u32_e32 v235, vcc, 0, v235, vcc
	global_load_dwordx4 v[224:227], v[234:235], off offset:2880
	global_load_dwordx4 v[228:231], v[234:235], off offset:3392
	v_lshlrev_b16_e32 v16, 5, v7
	v_lshlrev_b32_e32 v20, 5, v7
	v_ashrrev_i32_e32 v17, 2, v1
	s_load_dwordx2 s[4:5], s[16:17], 0x68
	s_load_dwordx2 s[6:7], s[16:17], 0x90
	v_bfe_u32 v63, v62, 6, 2
	v_and_b32_e32 v30, 63, v62
	s_mov_b32 s71, 0
	s_waitcnt vmcnt(9)
	v_mul_f32_e32 v7, 0xbfb8aa3b, v6
	s_waitcnt vmcnt(8)
	v_mul_f32_e32 v9, 0xbfb8aa3b, v2
	v_fma_f32 v10, v6, s33, -v7
	v_rndne_f32_e32 v11, v7
	v_fma_f32 v12, v2, s33, -v9
	v_rndne_f32_e32 v13, v9
	v_fmac_f32_e32 v10, 0xb2a5705f, v6
	v_sub_f32_e32 v7, v7, v11
	v_fmac_f32_e32 v12, 0xb2a5705f, v2
	v_sub_f32_e32 v9, v9, v13
	v_add_f32_e32 v7, v7, v10
	v_cvt_i32_f32_e32 v11, v11
	v_add_f32_e32 v9, v9, v12
	v_exp_f32_e32 v7, v7
	v_cvt_i32_f32_e32 v13, v13
	v_exp_f32_e32 v9, v9
	v_cmp_nlt_f32_e32 vcc, s52, v6
	v_ldexp_f32 v7, v7, v11
	v_ldexp_f32 v9, v9, v13
	v_cndmask_b32_e32 v7, 0, v7, vcc
	v_cmp_nlt_f32_e32 vcc, s52, v2
	s_nop 1
	v_cndmask_b32_e32 v9, 0, v9, vcc
	v_cmp_ngt_f32_e32 vcc, s53, v6
	s_nop 1
	v_cndmask_b32_e32 v12, v50, v7, vcc
	v_cmp_ngt_f32_e32 vcc, s53, v2
	v_add_f32_e32 v2, 1.0, v12
	v_frexp_mant_f32_e32 v14, v2
	v_cndmask_b32_e32 v18, v50, v9, vcc
	v_add_f32_e32 v13, 1.0, v18
	v_add_f32_e32 v9, -1.0, v2
	v_cvt_f64_f32_e32 v[6:7], v2
	v_cvt_f64_f32_e32 v[10:11], v13
	v_sub_f32_e32 v21, v9, v2
	v_frexp_exp_i32_f64_e32 v6, v[6:7]
	v_cmp_gt_f32_e32 vcc, s55, v14
	v_sub_f32_e32 v9, v12, v9
	v_frexp_exp_i32_f64_e32 v10, v[10:11]
	v_add_f32_e32 v11, 1.0, v21
	v_subbrev_co_u32_e32 v6, vcc, 0, v6, vcc
	v_add_f32_e32 v15, -1.0, v13
	v_add_f32_e32 v9, v9, v11
	v_sub_u32_e32 v11, 0, v6
	v_sub_f32_e32 v7, v15, v13
	v_cvt_f32_i32_e32 v6, v6
	v_ldexp_f32 v2, v2, v11
	v_sub_f32_e32 v15, v18, v15
	v_add_f32_e32 v7, 1.0, v7
	v_ldexp_f32 v9, v9, v11
	v_add_f32_e32 v11, -1.0, v2
	v_add_f32_e32 v14, 1.0, v2
	v_add_f32_e32 v7, v15, v7
	v_add_f32_e32 v15, 1.0, v11
	v_add_f32_e32 v21, -1.0, v14
	v_sub_f32_e32 v15, v2, v15
	v_sub_f32_e32 v2, v2, v21
	v_mul_f32_e32 v21, 0x3f317218, v6
	v_add_f32_e32 v15, v9, v15
	v_add_f32_e32 v2, v9, v2
	v_fma_f32 v9, v6, s56, -v21
	v_add_f32_e32 v22, v11, v15
	v_add_f32_e32 v23, v14, v2
	v_fmac_f32_e32 v9, 0xb102e308, v6
	v_sub_f32_e32 v6, v11, v22
	v_sub_f32_e32 v11, v14, v23
	v_rcp_f32_e32 v14, v23
	v_add_f32_e32 v24, v21, v9
	v_add_f32_e32 v2, v2, v11
	v_sub_f32_e32 v11, v24, v21
	v_sub_f32_e32 v9, v9, v11
	v_mul_f32_e32 v11, v22, v14
	v_add_f32_e32 v6, v15, v6
	v_mul_f32_e32 v15, v23, v11
	v_fma_f32 v21, v11, v23, -v15
	v_fmac_f32_e32 v21, v11, v2
	v_add_f32_e32 v25, v15, v21
	v_sub_f32_e32 v26, v22, v25
	v_sub_f32_e32 v15, v25, v15
	v_sub_f32_e32 v22, v22, v26
	v_sub_f32_e32 v15, v15, v21
	v_sub_f32_e32 v21, v22, v25
	v_add_f32_e32 v6, v6, v21
	v_add_f32_e32 v6, v15, v6
	v_add_f32_e32 v15, v26, v6
	v_mul_f32_e32 v21, v14, v15
	v_sub_f32_e32 v22, v26, v15
	v_mul_f32_e32 v25, v23, v21
	v_add_f32_e32 v6, v6, v22
	v_add_f32_e32 v22, v11, v21
	v_fma_f32 v23, v21, v23, -v25
	v_sub_f32_e32 v11, v22, v11
	v_fmac_f32_e32 v23, v21, v2
	v_sub_f32_e32 v2, v21, v11
	v_add_f32_e32 v11, v25, v23
	v_sub_f32_e32 v21, v11, v25
	v_sub_f32_e32 v25, v15, v11
	v_sub_f32_e32 v15, v15, v25
	v_sub_f32_e32 v11, v15, v11
	v_sub_f32_e32 v21, v21, v23
	v_add_f32_e32 v6, v6, v11
	v_add_f32_e32 v6, v21, v6
	v_add_f32_e32 v6, v25, v6
	v_mul_f32_e32 v6, v14, v6
	v_add_f32_e32 v2, v2, v6
	v_add_f32_e32 v6, v22, v2
	v_mul_f32_e32 v11, v6, v6
	v_fmamk_f32 v21, v11, 0x3e9b6dac, v51
	v_sub_f32_e32 v14, v6, v22
	v_ldexp_f32 v15, v6, 1
	v_mul_f32_e32 v6, v6, v11
	v_fmaak_f32 v11, v11, v21, 0x3f2aaada
	v_mul_f32_e32 v6, v6, v11
	v_add_f32_e32 v11, v15, v6
	v_sub_f32_e32 v2, v2, v14
	v_sub_f32_e32 v14, v11, v15
	v_ldexp_f32 v2, v2, 1
	v_sub_f32_e32 v6, v6, v14
	v_add_f32_e32 v2, v2, v6
	v_add_f32_e32 v6, v11, v2
	v_sub_f32_e32 v11, v6, v11
	v_add_f32_e32 v14, v24, v6
	v_sub_f32_e32 v2, v2, v11
	v_sub_f32_e32 v11, v14, v24
	v_sub_f32_e32 v15, v14, v11
	v_sub_f32_e32 v6, v6, v11
	v_add_f32_e32 v11, v9, v2
	v_sub_f32_e32 v15, v24, v15
	v_sub_f32_e32 v21, v11, v9
	v_add_f32_e32 v6, v6, v15
	v_sub_f32_e32 v15, v11, v21
	v_sub_f32_e32 v2, v2, v21
	v_sub_f32_e32 v9, v9, v15
	v_add_f32_e32 v6, v11, v6
	v_add_f32_e32 v2, v2, v9
	v_add_f32_e32 v9, v14, v6
	v_sub_f32_e32 v11, v9, v14
	v_sub_f32_e32 v6, v6, v11
	v_add_f32_e32 v2, v2, v6
	v_add_f32_e32 v2, v9, v2
	v_cmp_neq_f32_e32 vcc, s54, v12
	v_frexp_mant_f32_e32 v19, v13
	s_nop 0
	v_cndmask_b32_e32 v2, v50, v2, vcc
	v_cmp_lt_f32_e64 vcc, |v12|, s57
	s_nop 1
	v_cndmask_b32_e32 v9, v2, v12, vcc
	v_cmp_gt_f32_e32 vcc, s55, v19
	s_nop 1
	v_subbrev_co_u32_e32 v19, vcc, 0, v10, vcc
	v_sub_u32_e32 v2, 0, v19
	v_ldexp_f32 v6, v13, v2
	v_ldexp_f32 v2, v7, v2
	v_add_f32_e32 v7, -1.0, v6
	v_add_f32_e32 v12, 1.0, v6
	v_add_f32_e32 v10, 1.0, v7
	v_add_f32_e32 v13, -1.0, v12
	v_sub_f32_e32 v10, v6, v10
	v_sub_f32_e32 v6, v6, v13
	v_add_f32_e32 v10, v2, v10
	v_add_f32_e32 v2, v2, v6
	v_add_f32_e32 v6, v12, v2
	v_rcp_f32_e32 v13, v6
	v_add_f32_e32 v11, v7, v10
	v_sub_f32_e32 v7, v7, v11
	v_add_f32_e32 v7, v10, v7
	v_sub_f32_e32 v10, v12, v6
	v_add_f32_e32 v2, v2, v10
	v_mul_f32_e32 v10, v11, v13
	v_mul_f32_e32 v12, v6, v10
	v_fma_f32 v14, v10, v6, -v12
	v_fmac_f32_e32 v14, v10, v2
	v_add_f32_e32 v15, v12, v14
	v_sub_f32_e32 v21, v11, v15
	v_sub_f32_e32 v11, v11, v21
	v_sub_f32_e32 v12, v15, v12
	v_sub_f32_e32 v11, v11, v15
	v_add_f32_e32 v7, v7, v11
	v_sub_f32_e32 v11, v12, v14
	v_add_f32_e32 v7, v11, v7
	v_add_f32_e32 v11, v21, v7
	v_mul_f32_e32 v12, v13, v11
	v_mul_f32_e32 v14, v6, v12
	v_fma_f32 v6, v12, v6, -v14
	v_fmac_f32_e32 v6, v12, v2
	v_sub_f32_e32 v2, v21, v11
	v_add_f32_e32 v2, v7, v2
	v_add_f32_e32 v7, v14, v6
	v_sub_f32_e32 v15, v11, v7
	v_sub_f32_e32 v11, v11, v15
	v_sub_f32_e32 v14, v7, v14
	v_sub_f32_e32 v7, v11, v7
	v_add_f32_e32 v2, v2, v7
	v_sub_f32_e32 v6, v14, v6
	v_add_f32_e32 v2, v6, v2
	v_add_f32_e32 v22, v10, v12
	v_add_f32_e32 v2, v15, v2
	v_sub_f32_e32 v6, v22, v10
	v_mul_f32_e32 v2, v13, v2
	v_sub_f32_e32 v6, v12, v6
	v_add_f32_e32 v23, v6, v2
	v_lshlrev_b32_e32 v2, 3, v62
	v_and_b32_e32 v26, 56, v2
	v_lshlrev_b32_e32 v2, 7, v8
	v_lshl_add_u64 v[6:7], s[22:23], 0, v[2:3]
	v_lshlrev_b32_e32 v2, 1, v26
	v_lshlrev_b32_e32 v21, 7, v17
	v_lshl_add_u64 v[6:7], v[6:7], 0, v[2:3]
	v_bfe_u32 v2, v62, 3, 5
	v_or_b32_e32 v10, v2, v21
	v_mad_i64_i32 v[14:15], s[2:3], v10, s58, v[6:7]
	s_waitcnt vmcnt(7)
	v_mov_b32_e32 v10, v200
	v_mov_b32_e32 v11, v201
	v_mov_b32_e32 v12, v202
	v_mov_b32_e32 v13, v203
	v_cvt_f32_i32_e32 v19, v19
	v_add_f32_e32 v24, v22, v23
	v_mul_f32_e32 v25, v24, v24
	v_fmamk_f32 v27, v25, 0x3e9b6dac, v51
	v_mul_f32_e32 v28, 0x3f317218, v19
	v_fma_f32 v29, v19, s56, -v28
	v_fmac_f32_e32 v29, 0xb102e308, v19
	v_sub_f32_e32 v19, v24, v22
	v_add_f32_e32 v31, v28, v29
	v_fmaak_f32 v27, v25, v27, 0x3f2aaada
	v_sub_f32_e32 v19, v23, v19
	v_sub_f32_e32 v22, v31, v28
	v_mul_f32_e32 v23, v24, v25
	v_sub_f32_e32 v28, v29, v22
	v_ldexp_f32 v22, v24, 1
	v_mul_f32_e32 v23, v23, v27
	v_add_f32_e32 v24, v22, v23
	v_sub_f32_e32 v22, v24, v22
	v_ldexp_f32 v19, v19, 1
	v_sub_f32_e32 v22, v23, v22
	v_add_f32_e32 v19, v19, v22
	v_add_f32_e32 v27, v24, v19
	v_sub_f32_e32 v22, v27, v24
	v_sub_f32_e32 v19, v19, v22
	s_waitcnt vmcnt(6)
	v_mov_b32_e32 v22, v204
	v_mov_b32_e32 v23, v205
	v_mov_b32_e32 v24, v206
	v_mov_b32_e32 v25, v207
	v_add_f32_e32 v29, v31, v27
	v_sub_f32_e32 v32, v29, v31
	v_sub_f32_e32 v33, v29, v32
	v_sub_f32_e32 v14, v31, v33
	v_sub_f32_e32 v15, v27, v32
	v_add_f32_e32 v14, v15, v14
	v_add_f32_e32 v15, v28, v19
	v_sub_f32_e32 v27, v15, v28
	v_add_f32_e32 v14, v15, v14
	v_sub_f32_e32 v31, v15, v27
	v_add_f32_e32 v15, v29, v14
	v_sub_f32_e32 v28, v28, v31
	v_sub_f32_e32 v19, v19, v27
	v_sub_f32_e32 v27, v15, v29
	v_add_f32_e32 v19, v19, v28
	v_sub_f32_e32 v14, v14, v27
	v_add_f32_e32 v14, v19, v14
	v_add_f32_e32 v14, v15, v14
	v_xor_b32_e32 v15, 0x7f, v2
	v_cvt_f32_ubyte0_e32 v15, v15
	v_mul_f32_e64 v15, v15, -v9
	v_mul_f32_e32 v19, 0x3fb8aa3b, v15
	v_fma_f32 v27, v15, s59, -v19
	v_rndne_f32_e32 v28, v19
	v_fmac_f32_e32 v27, 0x32a5705f, v15
	v_sub_f32_e32 v19, v19, v28
	v_add_f32_e32 v19, v19, v27
	v_exp_f32_e32 v19, v19
	v_cvt_i32_f32_e32 v27, v28
	v_cmp_neq_f32_e32 vcc, s54, v18
	v_or_b32_e32 v38, 32, v2
	v_mul_u32_u24_e32 v26, 0x88, v26
	v_cndmask_b32_e32 v14, v50, v14, vcc
	v_cmp_lt_f32_e64 vcc, |v18|, s57
	v_lshlrev_b32_e32 v26, 1, v26
	v_lshlrev_b32_e32 v32, 16, v12
	v_cndmask_b32_e32 v18, v14, v18, vcc
	v_ldexp_f32 v14, v19, v27
	v_cvt_f32_ubyte0_e32 v19, v2
	v_mul_f32_e64 v19, v19, -v18
	v_mul_f32_e32 v27, 0x3fb8aa3b, v19
	v_fma_f32 v28, v19, s59, -v27
	v_rndne_f32_e32 v29, v27
	v_fmac_f32_e32 v28, 0x32a5705f, v19
	v_sub_f32_e32 v27, v27, v29
	v_add_f32_e32 v27, v27, v28
	v_exp_f32_e32 v27, v27
	v_cvt_i32_f32_e32 v28, v29
	v_cmp_ngt_f32_e32 vcc, s60, v15
	v_and_b32_e32 v33, 0xffff0000, v12
	v_lshlrev_b32_e32 v34, 16, v13
	v_cndmask_b32_e32 v14, 0, v14, vcc
	v_cmp_nlt_f32_e32 vcc, s61, v15
	v_and_b32_e32 v35, 0xffff0000, v13
	v_lshlrev_b32_e32 v29, 1, v2
	v_cndmask_b32_e32 v14, v50, v14, vcc
	v_mul_f32_e32 v31, 0x3e000000, v14
	v_ldexp_f32 v14, v27, v28
	v_cmp_ngt_f32_e32 vcc, s60, v19
	v_lshlrev_b32_e32 v27, 16, v11
	v_and_b32_e32 v28, 0xffff0000, v11
	v_cndmask_b32_e32 v14, 0, v14, vcc
	v_cmp_nlt_f32_e32 vcc, s61, v19
	v_add3_u32 v39, v48, v29, v26
	v_mul_f32_e32 v26, v31, v28
	v_cndmask_b32_e32 v14, v50, v14, vcc
	v_mul_f32_e32 v19, 0x3e000000, v14
	v_lshlrev_b32_e32 v14, 16, v10
	v_and_b32_e32 v10, 0xffff0000, v10
	v_mul_f32_e32 v11, v31, v14
	v_mul_f32_e32 v12, v31, v10
	v_mul_f32_e32 v10, v19, v10
	v_cvt_pk_bf16_f32 v36, v11, v12
	v_mul_f32_e32 v11, v19, v14
	v_cvt_pk_bf16_f32 v37, v11, v10
	v_or_b32_e32 v10, v38, v21
	v_mad_i64_i32 v[14:15], s[2:3], v10, s58, v[6:7]
	s_waitcnt vmcnt(5)
	v_mov_b32_e32 v10, v208
	v_mov_b32_e32 v11, v209
	v_mov_b32_e32 v12, v210
	v_mov_b32_e32 v13, v211
	ds_write_b16 v39, v36
	ds_write_b16_d16_hi v39, v36 offset:272
	ds_write_b16 v39, v37 offset:17408
	ds_write_b16_d16_hi v39, v37 offset:17680
	ds_write_b16 v39, v22 offset:34816
	ds_write_b16_d16_hi v39, v22 offset:35088
	v_mul_f32_e32 v22, v31, v27
	v_cvt_pk_bf16_f32 v22, v22, v26
	v_mul_f32_e32 v26, v19, v27
	v_mul_f32_e32 v27, v19, v28
	v_cvt_pk_bf16_f32 v26, v26, v27
	ds_write_b16 v39, v22 offset:544
	ds_write_b16_d16_hi v39, v22 offset:816
	ds_write_b16 v39, v26 offset:17952
	ds_write_b16_d16_hi v39, v26 offset:18224
	ds_write_b16 v39, v23 offset:35360
	ds_write_b16_d16_hi v39, v23 offset:35632
	s_waitcnt vmcnt(4)
	v_mov_b32_e32 v26, v212
	v_mov_b32_e32 v27, v213
	v_mov_b32_e32 v28, v214
	v_mov_b32_e32 v29, v215
	v_mul_f32_e32 v22, v31, v32
	v_mul_f32_e32 v14, v31, v33
	v_mul_f32_e32 v15, v19, v32
	v_cvt_pk_bf16_f32 v14, v22, v14
	v_mul_f32_e32 v22, v19, v33
	v_cvt_pk_bf16_f32 v15, v15, v22
	ds_write_b16 v39, v14 offset:1088
	ds_write_b16_d16_hi v39, v14 offset:1360
	ds_write_b16 v39, v15 offset:18496
	ds_write_b16_d16_hi v39, v15 offset:18768
	ds_write_b16 v39, v24 offset:35904
	ds_write_b16_d16_hi v39, v24 offset:36176
	v_mul_f32_e32 v14, v31, v34
	v_mul_f32_e32 v15, v31, v35
	v_cvt_pk_bf16_f32 v14, v14, v15
	v_mul_f32_e32 v15, v19, v34
	v_mul_f32_e32 v19, v19, v35
	v_cvt_pk_bf16_f32 v15, v15, v19
	ds_write_b16 v39, v14 offset:1632
	ds_write_b16_d16_hi v39, v14 offset:1904
	ds_write_b16 v39, v15 offset:19040
	v_xor_b32_e32 v14, 0x5f, v2
	v_cvt_f32_ubyte0_e32 v14, v14
	v_mul_f32_e64 v14, v14, -v9
	v_mul_f32_e32 v19, 0x3fb8aa3b, v14
	v_fma_f32 v22, v14, s59, -v19
	v_rndne_f32_e32 v23, v19
	v_fmac_f32_e32 v22, 0x32a5705f, v14
	v_sub_f32_e32 v19, v19, v23
	v_add_f32_e32 v19, v19, v22
	v_exp_f32_e32 v19, v19
	v_cvt_i32_f32_e32 v22, v23
	ds_write_b16_d16_hi v39, v15 offset:19312
	ds_write_b16 v39, v25 offset:36448
	ds_write_b16_d16_hi v39, v25 offset:36720
	v_cmp_ngt_f32_e32 vcc, s60, v14
	v_or_b32_e32 v37, 64, v2
	v_ldexp_f32 v15, v19, v22
	v_cvt_f32_ubyte0_e32 v19, v38
	v_mul_f32_e64 v19, v19, -v18
	v_mul_f32_e32 v22, 0x3fb8aa3b, v19
	v_fma_f32 v23, v19, s59, -v22
	v_rndne_f32_e32 v24, v22
	v_fmac_f32_e32 v23, 0x32a5705f, v19
	v_sub_f32_e32 v22, v22, v24
	v_add_f32_e32 v22, v22, v23
	v_exp_f32_e32 v22, v22
	v_cvt_i32_f32_e32 v23, v24
	v_cndmask_b32_e32 v15, 0, v15, vcc
	v_cmp_nlt_f32_e32 vcc, s61, v14
	v_lshlrev_b32_e32 v24, 16, v11
	v_cndmask_b32_e32 v14, v50, v15, vcc
	v_mul_f32_e32 v31, 0x3e000000, v14
	v_ldexp_f32 v14, v22, v23
	v_cmp_ngt_f32_e32 vcc, s60, v19
	v_lshlrev_b32_e32 v22, 16, v10
	v_and_b32_e32 v23, 0xffff0000, v10
	v_cndmask_b32_e32 v14, 0, v14, vcc
	v_cmp_nlt_f32_e32 vcc, s61, v19
	v_mul_f32_e32 v10, v31, v22
	v_and_b32_e32 v25, 0xffff0000, v11
	v_cndmask_b32_e32 v14, v50, v14, vcc
	v_mul_f32_e32 v11, v31, v23
	v_cvt_pk_bf16_f32 v36, v10, v11
	v_or_b32_e32 v10, v37, v21
	v_mul_f32_e32 v19, 0x3e000000, v14
	v_mad_i64_i32 v[14:15], s[2:3], v10, s58, v[6:7]
	v_lshlrev_b32_e32 v32, 16, v12
	v_and_b32_e32 v33, 0xffff0000, v12
	v_lshlrev_b32_e32 v34, 16, v13
	v_and_b32_e32 v35, 0xffff0000, v13
	s_waitcnt vmcnt(3)
	v_mov_b32_e32 v10, v216
	v_mov_b32_e32 v11, v217
	v_mov_b32_e32 v12, v218
	v_mov_b32_e32 v13, v219
	v_mul_f32_e32 v22, v19, v22
	v_mul_f32_e32 v23, v19, v23
	v_cvt_pk_bf16_f32 v22, v22, v23
	ds_write_b16 v39, v36 offset:64
	ds_write_b16_d16_hi v39, v36 offset:336
	ds_write_b16 v39, v22 offset:17472
	ds_write_b16_d16_hi v39, v22 offset:17744
	ds_write_b16 v39, v26 offset:34880
	ds_write_b16_d16_hi v39, v26 offset:35152
	v_mul_f32_e32 v22, v31, v24
	v_mul_f32_e32 v23, v31, v25
	v_cvt_pk_bf16_f32 v22, v22, v23
	v_mul_f32_e32 v23, v19, v24
	v_mul_f32_e32 v24, v19, v25
	v_cvt_pk_bf16_f32 v23, v23, v24
	ds_write_b16 v39, v22 offset:608
	ds_write_b16_d16_hi v39, v22 offset:880
	ds_write_b16 v39, v23 offset:18016
	ds_write_b16_d16_hi v39, v23 offset:18288
	ds_write_b16 v39, v27 offset:35424
	ds_write_b16_d16_hi v39, v27 offset:35696
	s_waitcnt vmcnt(2)
	v_mov_b32_e32 v22, v220
	v_mov_b32_e32 v23, v221
	v_mov_b32_e32 v24, v222
	v_mov_b32_e32 v25, v223
	v_mul_f32_e32 v26, v31, v32
	v_mul_f32_e32 v14, v31, v33
	v_mul_f32_e32 v15, v19, v32
	v_cvt_pk_bf16_f32 v14, v26, v14
	v_mul_f32_e32 v26, v19, v33
	v_cvt_pk_bf16_f32 v15, v15, v26
	ds_write_b16 v39, v14 offset:1152
	ds_write_b16_d16_hi v39, v14 offset:1424
	ds_write_b16 v39, v15 offset:18560
	ds_write_b16_d16_hi v39, v15 offset:18832
	ds_write_b16 v39, v28 offset:35968
	ds_write_b16_d16_hi v39, v28 offset:36240
	v_mul_f32_e32 v14, v31, v34
	v_mul_f32_e32 v15, v31, v35
	v_cvt_pk_bf16_f32 v14, v14, v15
	v_mul_f32_e32 v15, v19, v34
	v_mul_f32_e32 v19, v19, v35
	v_cvt_pk_bf16_f32 v15, v15, v19
	ds_write_b16 v39, v14 offset:1696
	ds_write_b16_d16_hi v39, v14 offset:1968
	ds_write_b16 v39, v15 offset:19104
	v_xor_b32_e32 v14, 63, v2
	v_cvt_f32_ubyte0_e32 v14, v14
	v_mul_f32_e64 v14, v14, -v9
	v_mul_f32_e32 v19, 0x3fb8aa3b, v14
	v_fma_f32 v26, v14, s59, -v19
	v_rndne_f32_e32 v27, v19
	v_fmac_f32_e32 v26, 0x32a5705f, v14
	v_sub_f32_e32 v19, v19, v27
	v_add_f32_e32 v19, v19, v26
	v_exp_f32_e32 v19, v19
	v_cvt_i32_f32_e32 v26, v27
	ds_write_b16_d16_hi v39, v15 offset:19376
	ds_write_b16 v39, v29 offset:36512
	ds_write_b16_d16_hi v39, v29 offset:36784
	v_cmp_ngt_f32_e32 vcc, s60, v14
	v_or_b32_e32 v35, 0x60, v2
	v_ldexp_f32 v15, v19, v26
	v_cvt_f32_ubyte0_e32 v19, v37
	v_mul_f32_e64 v19, v19, -v18
	v_mul_f32_e32 v26, 0x3fb8aa3b, v19
	v_fma_f32 v27, v19, s59, -v26
	v_rndne_f32_e32 v28, v26
	v_fmac_f32_e32 v27, 0x32a5705f, v19
	v_sub_f32_e32 v26, v26, v28
	v_add_f32_e32 v26, v26, v27
	v_exp_f32_e32 v26, v26
	v_cvt_i32_f32_e32 v27, v28
	v_cndmask_b32_e32 v15, 0, v15, vcc
	v_cmp_nlt_f32_e32 vcc, s61, v14
	v_xor_b32_e32 v2, 31, v2
	v_cvt_f32_ubyte0_e32 v2, v2
	v_cndmask_b32_e32 v14, v50, v15, vcc
	v_ldexp_f32 v15, v26, v27
	v_cmp_ngt_f32_e32 vcc, s60, v19
	v_mul_f32_e32 v14, 0x3e000000, v14
	v_mul_f32_e64 v2, v2, -v9
	v_cndmask_b32_e32 v15, 0, v15, vcc
	v_cmp_nlt_f32_e32 vcc, s61, v19
	v_lshlrev_b32_e32 v19, 16, v10
	v_and_b32_e32 v26, 0xffff0000, v10
	v_mul_f32_e32 v10, v14, v19
	v_lshlrev_b32_e32 v27, 16, v11
	v_and_b32_e32 v28, 0xffff0000, v11
	v_mul_f32_e32 v11, v14, v26
	v_cvt_pk_bf16_f32 v29, v10, v11
	v_or_b32_e32 v10, v35, v21
	v_mad_i64_i32 v[6:7], s[2:3], v10, s58, v[6:7]
	v_cndmask_b32_e32 v15, v50, v15, vcc
	v_lshlrev_b32_e32 v31, 16, v12
	v_and_b32_e32 v32, 0xffff0000, v12
	v_lshlrev_b32_e32 v33, 16, v13
	v_and_b32_e32 v34, 0xffff0000, v13
	s_waitcnt vmcnt(1)
	v_mov_b32_e32 v10, v224
	v_mov_b32_e32 v11, v225
	v_mov_b32_e32 v12, v226
	v_mov_b32_e32 v13, v227
	v_mul_f32_e32 v15, 0x3e000000, v15
	v_mul_f32_e32 v19, v15, v19
	v_mul_f32_e32 v26, v15, v26
	v_cvt_pk_bf16_f32 v19, v19, v26
	ds_write_b16 v39, v29 offset:128
	ds_write_b16_d16_hi v39, v29 offset:400
	ds_write_b16 v39, v19 offset:17536
	ds_write_b16_d16_hi v39, v19 offset:17808
	ds_write_b16 v39, v22 offset:34944
	ds_write_b16_d16_hi v39, v22 offset:35216
	v_mul_f32_e32 v19, v14, v27
	v_mul_f32_e32 v22, v14, v28
	v_cvt_pk_bf16_f32 v19, v19, v22
	v_mul_f32_e32 v22, v15, v27
	v_mul_f32_e32 v26, v15, v28
	ds_write_b16 v39, v19 offset:672
	ds_write_b16_d16_hi v39, v19 offset:944
	v_cvt_pk_bf16_f32 v22, v22, v26
	s_waitcnt vmcnt(0)
	v_mov_b32_e32 v26, v228
	v_mov_b32_e32 v27, v229
	v_mov_b32_e32 v28, v230
	v_mov_b32_e32 v29, v231
	v_mul_f32_e32 v6, v14, v31
	v_mul_f32_e32 v7, v14, v32
	v_cvt_pk_bf16_f32 v6, v6, v7
	v_mul_f32_e32 v7, v15, v31
	v_mul_f32_e32 v19, v15, v32
	v_cvt_pk_bf16_f32 v7, v7, v19
	ds_write_b16 v39, v22 offset:18080
	ds_write_b16_d16_hi v39, v22 offset:18352
	ds_write_b16 v39, v23 offset:35488
	ds_write_b16_d16_hi v39, v23 offset:35760
	ds_write_b16 v39, v6 offset:1216
	ds_write_b16_d16_hi v39, v6 offset:1488
	ds_write_b16 v39, v7 offset:18624
	ds_write_b16_d16_hi v39, v7 offset:18896
	ds_write_b16 v39, v24 offset:36032
	ds_write_b16_d16_hi v39, v24 offset:36304
	v_mul_f32_e32 v6, v14, v33
	v_mul_f32_e32 v7, v14, v34
	v_cvt_pk_bf16_f32 v6, v6, v7
	v_mul_f32_e32 v7, v15, v33
	v_mul_f32_e32 v14, v15, v34
	v_cvt_pk_bf16_f32 v7, v7, v14
	ds_write_b16 v39, v6 offset:1760
	ds_write_b16_d16_hi v39, v6 offset:2032
	ds_write_b16 v39, v7 offset:19168
	v_mul_f32_e32 v6, 0x3fb8aa3b, v2
	v_fma_f32 v9, v2, s59, -v6
	v_rndne_f32_e32 v14, v6
	v_fmac_f32_e32 v9, 0x32a5705f, v2
	v_sub_f32_e32 v6, v6, v14
	v_add_f32_e32 v6, v6, v9
	v_exp_f32_e32 v6, v6
	v_cvt_i32_f32_e32 v9, v14
	ds_write_b16_d16_hi v39, v7 offset:19440
	ds_write_b16 v39, v25 offset:36576
	ds_write_b16_d16_hi v39, v25 offset:36848
	v_cvt_f32_ubyte0_e32 v7, v35
	v_mul_f32_e64 v7, v7, -v18
	v_ldexp_f32 v6, v6, v9
	v_mul_f32_e32 v9, 0x3fb8aa3b, v7
	v_fma_f32 v14, v7, s59, -v9
	v_rndne_f32_e32 v15, v9
	v_fmac_f32_e32 v14, 0x32a5705f, v7
	v_sub_f32_e32 v9, v9, v15
	v_add_f32_e32 v9, v9, v14
	v_exp_f32_e32 v9, v9
	v_cvt_i32_f32_e32 v14, v15
	v_cmp_ngt_f32_e32 vcc, s60, v2
	v_lshlrev_b32_e32 v22, 3, v63
	v_or3_b32 v20, v21, v20, v22
	v_cndmask_b32_e32 v6, 0, v6, vcc
	v_cmp_nlt_f32_e32 vcc, s61, v2
	v_lshlrev_b32_e32 v32, 3, v30
	v_mov_b32_e32 v33, v3
	v_cndmask_b32_e32 v2, v50, v6, vcc
	v_ldexp_f32 v6, v9, v14
	v_cmp_ngt_f32_e32 vcc, s60, v7
	v_mul_f32_e32 v2, 0x3e000000, v2
	v_cmp_eq_u32_e64 s[2:3], 0, v30
	v_cndmask_b32_e32 v6, 0, v6, vcc
	v_cmp_nlt_f32_e32 vcc, s61, v7
	v_lshlrev_b32_e32 v7, 16, v10
	v_cndmask_b32_e32 v6, v50, v6, vcc
	v_mul_f32_e32 v6, 0x3e000000, v6
	v_and_b32_e32 v9, 0xffff0000, v10
	v_mul_f32_e32 v18, v2, v7
	v_mul_f32_e32 v7, v6, v7
	v_lshlrev_b32_e32 v10, 16, v11
	v_and_b32_e32 v11, 0xffff0000, v11
	v_mul_f32_e32 v19, v2, v9
	v_cvt_pk_bf16_f32 v18, v18, v19
	v_mul_f32_e32 v9, v6, v9
	v_cvt_pk_bf16_f32 v7, v7, v9
	ds_write_b16 v39, v18 offset:192
	ds_write_b16_d16_hi v39, v18 offset:464
	ds_write_b16 v39, v7 offset:17600
	ds_write_b16_d16_hi v39, v7 offset:17872
	ds_write_b16 v39, v26 offset:35008
	ds_write_b16_d16_hi v39, v26 offset:35280
	v_mul_f32_e32 v7, v2, v10
	v_mul_f32_e32 v9, v2, v11
	v_cvt_pk_bf16_f32 v7, v7, v9
	v_mul_f32_e32 v9, v6, v10
	v_lshlrev_b32_e32 v14, 16, v12
	v_and_b32_e32 v12, 0xffff0000, v12
	v_mul_f32_e32 v10, v6, v11
	v_cvt_pk_bf16_f32 v9, v9, v10
	ds_write_b16 v39, v7 offset:736
	ds_write_b16_d16_hi v39, v7 offset:1008
	ds_write_b16 v39, v9 offset:18144
	ds_write_b16_d16_hi v39, v9 offset:18416
	ds_write_b16 v39, v27 offset:35552
	ds_write_b16_d16_hi v39, v27 offset:35824
	v_mul_f32_e32 v7, v2, v14
	v_mul_f32_e32 v9, v2, v12
	v_lshlrev_b32_e32 v15, 16, v13
	v_and_b32_e32 v13, 0xffff0000, v13
	v_cvt_pk_bf16_f32 v7, v7, v9
	v_mul_f32_e32 v9, v6, v14
	v_mul_f32_e32 v10, v6, v12
	v_cvt_pk_bf16_f32 v9, v9, v10
	ds_write_b16 v39, v7 offset:1280
	ds_write_b16_d16_hi v39, v7 offset:1552
	ds_write_b16 v39, v9 offset:18688
	ds_write_b16_d16_hi v39, v9 offset:18960
	ds_write_b16 v39, v28 offset:36096
	ds_write_b16_d16_hi v39, v28 offset:36368
	v_mul_f32_e32 v7, v2, v15
	v_mul_f32_e32 v2, v2, v13
	v_cvt_pk_bf16_f32 v2, v7, v2
	v_mul_f32_e32 v7, v6, v15
	v_mul_f32_e32 v6, v6, v13
	v_cvt_pk_bf16_f32 v6, v7, v6
	v_lshlrev_b32_e32 v18, 5, v8
	v_cmp_lt_i32_e32 vcc, v55, v54
	ds_write_b16 v39, v2 offset:1824
	ds_write_b16_d16_hi v39, v2 offset:2096
	ds_write_b16 v39, v6 offset:19232
	ds_write_b16_d16_hi v39, v6 offset:19504
	ds_write_b16 v39, v29 offset:36640
	ds_write_b16_d16_hi v39, v29 offset:36912
	v_cndmask_b32_e32 v6, v53, v55, vcc
	v_cmp_lt_i32_e32 vcc, v56, v54
	v_lshlrev_b32_e32 v19, 8, v17
	v_or3_b32 v71, v18, v22, v21
	v_lshlrev_b16_e32 v17, 7, v17
	v_lshlrev_b16_e32 v18, 3, v63
	v_lshlrev_b32_e32 v64, 2, v6
	v_cndmask_b32_e32 v6, v53, v56, vcc
	v_cmp_lt_i32_e32 vcc, v57, v54
	v_bitop3_b16 v16, v17, v16, v18 bitop3:0xfe
	v_lshlrev_b32_e32 v65, 2, v6
	v_cndmask_b32_e32 v6, v53, v57, vcc
	v_cmp_lt_i32_e32 vcc, v58, v54
	v_and_b32_e32 v72, 0x7f8, v16
	v_and_b32_e32 v16, 0xf8, v16
	v_lshlrev_b32_e32 v66, 2, v6
	v_cndmask_b32_e32 v6, v53, v58, vcc
	v_cmp_lt_i32_e32 vcc, v59, v54
	v_or3_b32 v18, v19, v16, s62
	v_lshlrev_b32_e32 v67, 2, v6
	v_cndmask_b32_e32 v6, v53, v59, vcc
	v_cmp_lt_i32_e32 vcc, v60, v54
	v_lshlrev_b32_e32 v10, 4, v30
	v_mov_b32_e32 v11, v3
	v_ashrrev_i32_e32 v19, 31, v18
	v_lshlrev_b32_e32 v2, 2, v30
	v_lshlrev_b32_e32 v68, 2, v6
	v_cndmask_b32_e32 v6, v53, v60, vcc
	v_add_u32_e32 v8, 0xffffe000, v21
	s_waitcnt lgkmcnt(0)
	v_lshl_add_u64 v[10:11], s[6:7], 0, v[10:11]
	v_lshlrev_b64 v[16:17], 7, v[18:19]
	v_lshlrev_b64 v[18:19], 9, v[18:19]
	v_ashrrev_i32_e32 v21, 31, v20
	v_mad_i64_i32 v[26:27], s[6:7], v20, s58, 0
	v_lshlrev_b32_e32 v69, 2, v6
	v_lshl_add_u64 v[6:7], s[4:5], 0, v[32:33]
	v_lshrrev_b32_e32 v8, 3, v8
	v_cmp_gt_u32_e64 s[4:5], 32, v30
	v_or_b32_e32 v16, v16, v2
	v_or_b32_e32 v18, v18, v32
	v_lshlrev_b64 v[24:25], 11, v[20:21]
	v_or_b32_e32 v28, v26, v2
	v_mov_b32_e32 v29, v27
	v_lshl_or_b32 v30, v30, 1, v26
	v_mov_b32_e32 v31, v27
	v_and_b32_e32 v70, 0x1fffff00, v8
	v_lshl_add_u64 v[8:9], s[24:25], 0, v[2:3]
	v_lshl_add_u64 v[12:13], v[10:11], 0, s[34:35]
	v_lshl_add_u64 v[14:15], v[10:11], 0, s[36:37]
	v_lshl_add_u64 v[16:17], s[28:29], 0, v[16:17]
	v_lshl_add_u64 v[18:19], s[12:13], 0, v[18:19]
	v_lshl_add_u64 v[22:23], v[20:21], 2, v[4:5]
	v_or_b32_e32 v24, v24, v32
	v_lshl_add_u64 v[28:29], v[28:29], 0, s[38:39]
	v_lshl_add_u64 v[30:31], v[30:31], 0, s[40:41]
	v_or_b32_e32 v26, v26, v32
	s_branch .LBB0_1666

.LBB0_1867:
	v_lshlrev_b32_e32 v162, 4, v150
	v_mul_f32_e32 v168, v127, v127
	v_fmac_f32_e32 v168, v126, v126
	v_fmac_f32_e32 v168, v128, v128
	v_fmac_f32_e32 v168, v129, v129
	v_fmac_f32_e32 v168, v122, v122
	v_fmac_f32_e32 v168, v123, v123
	v_fmac_f32_e32 v168, v124, v124
	v_fmac_f32_e32 v168, v125, v125
	v_fmac_f32_e32 v168, v118, v118
	v_fmac_f32_e32 v168, v119, v119
	v_fmac_f32_e32 v168, v120, v120
	v_fmac_f32_e32 v168, v121, v121
	v_fmac_f32_e32 v168, v114, v114
	v_fmac_f32_e32 v168, v115, v115
	v_fmac_f32_e32 v168, v116, v116
	s_waitcnt vmcnt(14)
	v_pk_mul_f32 v[140:141], v[130:131], v[130:131]
	v_fmac_f32_e32 v168, v117, v117
	v_add_f32_e32 v140, v168, v140
	v_pk_mul_f32 v[144:145], v[132:133], v[132:133]
	v_add_f32_e32 v140, v141, v140
	v_add_f32_e32 v140, v144, v140
	v_and_b32_e32 v146, 64, v166
	v_pk_mul_f32 v[156:157], v[134:135], v[134:135]
	v_add_f32_e32 v140, v145, v140
	v_xor_b32_e32 v143, 16, v166
	v_add_u32_e32 v169, 64, v146
	v_add_f32_e32 v140, v156, v140
	v_pk_mul_f32 v[158:159], v[136:137], v[136:137]
	v_cmp_lt_i32_e32 vcc, v143, v169
	v_add_f32_e32 v140, v157, v140
	v_add_f32_e32 v140, v158, v140
	v_cndmask_b32_e32 v143, v166, v143, vcc
	v_lshlrev_b32_e32 v146, 2, v143
	v_add_f32_e32 v140, v159, v140
	v_mov_b32_e32 v141, v140
	s_nop 1
	v_permlane16_swap_b32_e32 v141, v140
	v_xor_b32_e32 v149, 32, v166
	v_cmp_lt_i32_e32 vcc, v149, v169
	v_lshrrev_b32_e32 v167, 6, v151
	s_lshl_b32 s2, s58, 2
	v_cndmask_b32_e32 v144, v166, v149, vcc
	v_lshlrev_b32_e32 v149, 2, v144
	s_waitcnt lgkmcnt(0)
	v_add_f32_e32 v141, v140, v141
	v_mov_b32_e32 v156, v141
	s_nop 1
	v_permlane32_swap_b32_e32 v156, v141
	v_mov_b64_e32 v[160:161], s[24:25]
	v_and_or_b32 v140, v167, 3, s2
	v_mad_i64_i32 v[144:145], s[2:3], v139, s57, v[160:161]
	s_waitcnt lgkmcnt(0)
	v_add_f32_e32 v139, v141, v156
	v_fmamk_f32 v139, v139, 0x3c2aaaab, v1
	v_mul_f32_e32 v141, 0x4b800000, v139
	v_cmp_gt_f32_e32 vcc, s56, v139
	v_mul_lo_u32 v140, v140, s55
	v_mov_b32_e32 v143, v163
	v_cndmask_b32_e32 v139, v139, v141, vcc
	v_rsq_f32_e32 v139, v139
	v_ashrrev_i32_e32 v141, 31, v140
	v_lshl_add_u64 v[144:145], v[140:141], 1, v[144:145]
	v_lshl_add_u64 v[156:157], v[144:145], 0, v[142:143]
	v_mul_f32_e32 v143, 0x45800000, v139
	v_cndmask_b32_e32 v158, v139, v143, vcc
	v_mul_f32_e32 v126, v126, v158
	v_mul_f32_e32 v127, v127, v158
	v_mul_f32_e32 v128, v128, v158
	v_mul_f32_e32 v129, v129, v158
	v_mul_f32_e32 v122, v122, v158
	v_mul_f32_e32 v123, v123, v158
	v_mul_f32_e32 v124, v124, v158
	v_mul_f32_e32 v125, v125, v158
	v_mul_f32_e32 v118, v118, v158
	v_mul_f32_e32 v119, v119, v158
	v_mul_f32_e32 v120, v120, v158
	v_mul_f32_e32 v121, v121, v158
	v_mul_f32_e32 v114, v114, v158
	v_mul_f32_e32 v115, v115, v158
	v_mul_f32_e32 v116, v116, v158
	v_mul_f32_e32 v117, v117, v158
	s_cmp_eq_u32 s62, 1
	v_cmp_gt_u32_e64 s[4:5], 2, v150
	s_cselect_b64 s[30:31], -1, 0
	v_mul_f32_e32 v126, v170, v126
	v_mul_f32_e32 v127, v171, v127
	v_mul_f32_e32 v128, v172, v128
	v_mul_f32_e32 v129, v173, v129
	v_cvt_pk_bf16_f32 v126, v126, v127
	v_cvt_pk_bf16_f32 v127, v128, v129
	global_store_dwordx2 v[156:157], v[126:127], off
	s_cmp_lg_u32 s62, 1
	v_mul_f32_e32 v122, v174, v122
	v_mul_f32_e32 v123, v175, v123
	v_mul_f32_e32 v124, v176, v124
	v_mul_f32_e32 v125, v177, v125
	v_cvt_pk_bf16_f32 v122, v122, v123
	v_cvt_pk_bf16_f32 v123, v124, v125
	global_store_dwordx2 v[156:157], v[122:123], off offset:32
	v_mul_f32_e32 v118, v178, v118
	v_mul_f32_e32 v119, v179, v119
	v_mul_f32_e32 v120, v180, v120
	v_mul_f32_e32 v121, v121, v181
	v_cvt_pk_bf16_f32 v118, v118, v119
	v_cvt_pk_bf16_f32 v119, v120, v121
	global_store_dwordx2 v[156:157], v[118:119], off offset:64
	v_and_b32_e32 v122, 16, v151
	v_cmp_eq_u32_e64 s[2:3], 0, v122
	v_mul_f32_e32 v114, v114, v182
	v_mul_f32_e32 v115, v115, v183
	v_mul_f32_e32 v116, v116, v184
	v_mul_f32_e32 v117, v117, v185
	v_cvt_pk_bf16_f32 v114, v114, v115
	v_cvt_pk_bf16_f32 v115, v116, v117
	global_store_dwordx2 v[156:157], v[114:115], off offset:96
	s_nop 0
	v_mov_b32_e32 v114, v186
	v_mov_b32_e32 v115, v187
	v_mov_b32_e32 v116, v188
	v_mov_b32_e32 v117, v189
	v_pk_mul_f32 v[114:115], v[158:159], v[114:115] op_sel_hi:[0,1]
	v_pk_mul_f32 v[116:117], v[158:159], v[116:117] op_sel_hi:[0,1]
	v_pk_mul_f32 v[122:123], v[158:159], v[190:191] op_sel_hi:[0,1]
	v_pk_mul_f32 v[124:125], v[158:159], v[192:193] op_sel_hi:[0,1]
	v_pk_mul_f32 v[120:121], v[130:131], v[114:115]
	v_pk_mul_f32 v[118:119], v[132:133], v[116:117]
	v_pk_mul_f32 v[116:117], v[134:135], v[122:123]
	v_pk_mul_f32 v[114:115], v[136:137], v[124:125]
	s_cbranch_scc1 .LBB0_1869
	v_add_u32_e32 v122, s60, v147
	v_ashrrev_i32_e32 v123, 6, v122
	v_and_b32_e32 v122, 63, v122
	v_cndmask_b32_e64 v122, v122, v123, s[4:5]
	v_cvt_f32_i32_e32 v130, v122
	ds_bpermute_b32 v122, v146, v120
	ds_bpermute_b32 v123, v146, v121
	v_mul_f32_e32 v125, 0x3ea1e89b, v130
	v_mul_f32_e32 v126, 0.15915494, v130
	v_mul_f32_e32 v127, 0.15915494, v125
	v_sin_f32_e32 v124, v126
	v_sin_f32_e32 v125, v127
	v_mul_f32_e32 v129, 0x3d0186e3, v130
	v_mul_f32_e32 v132, 0.15915494, v129
	v_cos_f32_e32 v126, v126
	s_waitcnt lgkmcnt(0)
	v_pk_mul_f32 v[122:123], v[124:125], v[122:123]
	v_mul_f32_e32 v125, 0x3dcccccd, v130
	ds_bpermute_b32 v124, v146, v118
	v_mul_f32_e32 v131, 0.15915494, v125
	ds_bpermute_b32 v125, v146, v119
	v_cos_f32_e32 v127, v127
	v_sin_f32_e32 v128, v131
	v_sin_f32_e32 v129, v132
	v_cndmask_b32_e64 v123, v123, -v123, s[2:3]
	v_cndmask_b32_e64 v122, v122, -v122, s[2:3]
	v_pk_fma_f32 v[120:121], v[126:127], v[120:121], v[122:123]
	s_waitcnt lgkmcnt(0)
	v_pk_mul_f32 v[124:125], v[128:129], v[124:125]
	v_mul_f32_e32 v127, 0x3c23d70b, v130
	v_mul_f32_e32 v129, 0x3b4f3e39, v130
	v_cos_f32_e32 v122, v131
	v_cos_f32_e32 v123, v132
	ds_bpermute_b32 v126, v146, v116
	v_mul_f32_e32 v131, 0.15915494, v127
	ds_bpermute_b32 v127, v146, v117
	v_mul_f32_e32 v132, 0.15915494, v129
	v_sin_f32_e32 v128, v131
	v_sin_f32_e32 v129, v132
	v_cndmask_b32_e64 v125, v125, -v125, s[2:3]
	v_cndmask_b32_e64 v124, v124, -v124, s[2:3]
	v_pk_fma_f32 v[118:119], v[122:123], v[118:119], v[124:125]
	v_cos_f32_e32 v122, v131
	v_cos_f32_e32 v123, v132
	s_waitcnt lgkmcnt(0)
	v_pk_mul_f32 v[124:125], v[128:129], v[126:127]
	v_mul_f32_e32 v127, 0x3a831270, v130
	v_mul_f32_e32 v129, 0x39a5cb61, v130
	ds_bpermute_b32 v126, v146, v114
	v_mul_f32_e32 v131, 0.15915494, v127
	ds_bpermute_b32 v127, v146, v115
	v_mul_f32_e32 v130, 0.15915494, v129
	v_sin_f32_e32 v128, v131
	v_sin_f32_e32 v129, v130
	v_cndmask_b32_e64 v125, v125, -v125, s[2:3]
	v_cndmask_b32_e64 v124, v124, -v124, s[2:3]
	v_pk_fma_f32 v[116:117], v[122:123], v[116:117], v[124:125]
	v_cos_f32_e32 v122, v131
	v_cos_f32_e32 v123, v130
	s_waitcnt lgkmcnt(0)
	v_pk_mul_f32 v[124:125], v[128:129], v[126:127]
	s_nop 0
	v_cndmask_b32_e64 v125, v125, -v125, s[2:3]
	v_cndmask_b32_e64 v124, v124, -v124, s[2:3]
	v_pk_fma_f32 v[114:115], v[122:123], v[114:115], v[124:125]
